# merge phase: K-part VGPRs re-allocated, 7 of 16 blocks of the running merged tile kept in registers (packed bf16) instead of global read-modify-write
# speedup vs baseline: 1.0191x; 1.0191x over previous
.LBB0_1018:
	s_ashr_i32 s15, s14, 31
	s_ashr_i32 s13, s12, 31
	s_lshl_b64 s[16:17], s[14:15], 19
	s_lshl_b64 s[18:19], s[12:13], 9
	s_add_u32 s13, s34, s16
	s_addc_u32 s15, s35, s17
	s_add_u32 s16, s13, s18
	s_addc_u32 s17, s15, s19
	s_and_b64 s[18:19], s[2:3], exec
	s_cselect_b32 s29, s17, s23
	s_cselect_b32 s28, s16, s22
	s_lshl_b32 s13, s12, 2
	s_add_i32 s18, s13, s51
	s_ashr_i32 s19, s18, 31
	s_lshl_b64 s[18:19], s[18:19], 17
	s_add_u32 s18, s36, s18
	s_addc_u32 s19, s37, s19
	s_and_b64 s[26:27], s[2:3], exec
	s_cselect_b32 s27, s19, s25
	s_cselect_b32 s26, s18, s24
	s_add_i32 s15, 0, 0x10000
	s_add_i32 s21, 0, 0x14000
	v_add_u32_e32 v253, s15, v174
	v_add_u32_e32 v252, s21, v174
	ds_read_b128 v[128:131], v253
	ds_read_b128 v[132:135], v253 offset:1024
	ds_read_b128 v[136:139], v253 offset:2048
	ds_read_b128 v[140:143], v253 offset:3072
	ds_read_b128 v[144:147], v252
	ds_read_b128 v[148:151], v252 offset:1024
	ds_read_b128 v[152:155], v252 offset:2048
	ds_read_b128 v[156:159], v252 offset:3072
	v_mov_b32_e32 v248, 0x1c000
	v_mov_b32_e32 v249, 0x3727c5ac
	v_mov_b64_e32 v[250:251], 0xff
	s_add_u32 s52, s22, 0x40080
	s_addc_u32 s53, s23, 0
	s_add_i32 s55, s39, 0xc000
	s_waitcnt vmcnt(0)
	v_lshl_add_u64 v[246:247], s[52:53], 0, v[160:161]
	s_mov_b32 m0, s55
	s_add_i32 s13, s39, 0xe000
	ds_read_b128 v[168:171], v175
	ds_read_b128 v[176:179], v175 offset:1024
	ds_read_b128 v[180:183], v175 offset:2048
	ds_read_b128 v[184:187], v175 offset:3072
	ds_read_b128 v[188:191], v175 offset:4096
	ds_read_b128 v[192:195], v175 offset:5120
	ds_read_b128 v[196:199], v175 offset:6144
	ds_read_b128 v[228:231], v175 offset:7168
	global_load_lds_dwordx4 v[246:247], off
	v_lshl_add_u64 v[246:247], s[52:53], 0, v[162:163]
	s_mov_b32 m0, s13
	s_nop 0
	global_load_lds_dwordx4 v[246:247], off
	s_waitcnt vmcnt(8)
	s_waitcnt lgkmcnt(0)
	s_barrier
	s_setprio 1
	s_waitcnt lgkmcnt(0)
	v_mfma_f32_16x16x32_bf16 v[0:3], v[128:131], v[168:171], 0
	v_mfma_f32_16x16x32_bf16 v[4:7], v[136:139], v[168:171], 0
	v_mfma_f32_16x16x32_bf16 v[16:19], v[128:131], v[180:183], 0
	v_mfma_f32_16x16x32_bf16 v[20:23], v[136:139], v[180:183], 0
	v_mfma_f32_16x16x32_bf16 v[32:35], v[128:131], v[188:191], 0
	v_mfma_f32_16x16x32_bf16 v[36:39], v[136:139], v[188:191], 0
	v_mfma_f32_16x16x32_bf16 v[48:51], v[128:131], v[196:199], 0
	v_mfma_f32_16x16x32_bf16 v[52:55], v[136:139], v[196:199], 0
	v_mfma_f32_16x16x32_bf16 v[0:3], v[132:135], v[176:179], v[0:3]
	v_mfma_f32_16x16x32_bf16 v[4:7], v[140:143], v[176:179], v[4:7]
	v_mfma_f32_16x16x32_bf16 v[16:19], v[132:135], v[184:187], v[16:19]
	v_mfma_f32_16x16x32_bf16 v[20:23], v[140:143], v[184:187], v[20:23]
	v_mfma_f32_16x16x32_bf16 v[32:35], v[132:135], v[192:195], v[32:35]
	v_mfma_f32_16x16x32_bf16 v[36:39], v[140:143], v[192:195], v[36:39]
	v_mfma_f32_16x16x32_bf16 v[48:51], v[132:135], v[228:231], v[48:51]
	v_mfma_f32_16x16x32_bf16 v[52:55], v[140:143], v[228:231], v[52:55]
	s_setprio 0
	s_setprio 1
	v_mfma_f32_16x16x32_bf16 v[8:11], v[144:147], v[168:171], 0
	v_mfma_f32_16x16x32_bf16 v[12:15], v[152:155], v[168:171], 0
	v_mfma_f32_16x16x32_bf16 v[8:11], v[148:151], v[176:179], v[8:11]
	v_mfma_f32_16x16x32_bf16 v[12:15], v[156:159], v[176:179], v[12:15]
	v_mfma_f32_16x16x32_bf16 v[24:27], v[144:147], v[180:183], 0
	v_mfma_f32_16x16x32_bf16 v[28:31], v[152:155], v[180:183], 0
	v_mfma_f32_16x16x32_bf16 v[24:27], v[148:151], v[184:187], v[24:27]
	v_mfma_f32_16x16x32_bf16 v[28:31], v[156:159], v[184:187], v[28:31]
	v_mfma_f32_16x16x32_bf16 v[40:43], v[144:147], v[188:191], 0
	v_mfma_f32_16x16x32_bf16 v[44:47], v[152:155], v[188:191], 0
	v_mfma_f32_16x16x32_bf16 v[40:43], v[148:151], v[192:195], v[40:43]
	v_mfma_f32_16x16x32_bf16 v[44:47], v[156:159], v[192:195], v[44:47]
	v_mfma_f32_16x16x32_bf16 v[56:59], v[144:147], v[196:199], 0
	v_mfma_f32_16x16x32_bf16 v[60:63], v[152:155], v[196:199], 0
	v_mfma_f32_16x16x32_bf16 v[56:59], v[148:151], v[228:231], v[56:59]
	v_mfma_f32_16x16x32_bf16 v[60:63], v[156:159], v[228:231], v[60:63]
	s_setprio 0
	s_barrier
	s_add_i32 s53, s15, s38
	v_lshl_add_u64 v[246:247], s[24:25], 0, v[232:233]
	s_mov_b64 s[58:59], 0x100
	s_add_i32 s15, s53, 0x2000
	v_lshl_add_u64 v[244:245], v[246:247], 0, s[58:59]
	s_mov_b32 m0, s53
	v_lshl_add_u64 v[242:243], s[24:25], 0, v[164:165]
	s_add_u32 s56, s24, 0x10100
	ds_read_b128 v[168:171], v175 offset:16384
	ds_read_b128 v[176:179], v175 offset:17408
	ds_read_b128 v[180:183], v175 offset:18432
	ds_read_b128 v[184:187], v175 offset:19456
	ds_read_b128 v[188:191], v175 offset:20480
	ds_read_b128 v[192:195], v175 offset:21504
	ds_read_b128 v[196:199], v175 offset:22528
	ds_read_b128 v[228:231], v175 offset:23552
	global_load_lds_dwordx4 v[244:245], off
	v_lshl_add_u64 v[244:245], v[242:243], 0, s[58:59]
	s_mov_b32 m0, s15
	s_addc_u32 s57, s25, 0
	s_add_i32 s21, s21, s38
	global_load_lds_dwordx4 v[244:245], off
	v_lshl_add_u64 v[244:245], s[56:57], 0, v[232:233]
	s_mov_b32 m0, s21
	s_add_i32 s52, s21, 0x2000
	global_load_lds_dwordx4 v[244:245], off
	v_lshl_add_u64 v[244:245], s[56:57], 0, v[164:165]
	s_mov_b32 m0, s52
	v_lshl_add_u64 v[240:241], s[22:23], 0, v[160:161]
	global_load_lds_dwordx4 v[244:245], off
	v_lshl_add_u64 v[244:245], v[240:241], 0, s[58:59]
	s_mov_b32 m0, s39
	v_lshl_add_u64 v[238:239], s[22:23], 0, v[162:163]
	global_load_lds_dwordx4 v[244:245], off
	v_lshl_add_u64 v[244:245], v[238:239], 0, s[58:59]
	s_mov_b32 m0, s40
	s_nop 0
	global_load_lds_dwordx4 v[244:245], off
	s_waitcnt vmcnt(8)
	s_waitcnt lgkmcnt(0)
	s_barrier
	s_setprio 1
	s_waitcnt lgkmcnt(0)
	v_mfma_f32_16x16x32_bf16 v[64:67], v[128:131], v[168:171], 0
	v_mfma_f32_16x16x32_bf16 v[80:83], v[128:131], v[180:183], 0
	v_mfma_f32_16x16x32_bf16 v[96:99], v[128:131], v[188:191], 0
	v_mfma_f32_16x16x32_bf16 v[112:115], v[128:131], v[196:199], 0
	v_mfma_f32_16x16x32_bf16 v[64:67], v[132:135], v[176:179], v[64:67]
	v_mfma_f32_16x16x32_bf16 v[68:71], v[136:139], v[168:171], 0
	v_mfma_f32_16x16x32_bf16 v[80:83], v[132:135], v[184:187], v[80:83]
	v_mfma_f32_16x16x32_bf16 v[84:87], v[136:139], v[180:183], 0
	v_mfma_f32_16x16x32_bf16 v[96:99], v[132:135], v[192:195], v[96:99]
	v_mfma_f32_16x16x32_bf16 v[112:115], v[132:135], v[228:231], v[112:115]
	v_mfma_f32_16x16x32_bf16 v[116:119], v[136:139], v[196:199], 0
	v_mfma_f32_16x16x32_bf16 v[68:71], v[140:143], v[176:179], v[68:71]
	v_mfma_f32_16x16x32_bf16 v[84:87], v[140:143], v[184:187], v[84:87]
	v_mfma_f32_16x16x32_bf16 v[100:103], v[136:139], v[188:191], 0
	v_mfma_f32_16x16x32_bf16 v[116:119], v[140:143], v[228:231], v[116:119]
	v_mfma_f32_16x16x32_bf16 v[100:103], v[140:143], v[192:195], v[100:103]
	s_setprio 0
	s_setprio 1
	v_mfma_f32_16x16x32_bf16 v[72:75], v[144:147], v[168:171], 0
	v_mfma_f32_16x16x32_bf16 v[76:79], v[152:155], v[168:171], 0
	v_mfma_f32_16x16x32_bf16 v[72:75], v[148:151], v[176:179], v[72:75]
	v_mfma_f32_16x16x32_bf16 v[76:79], v[156:159], v[176:179], v[76:79]
	v_mfma_f32_16x16x32_bf16 v[88:91], v[144:147], v[180:183], 0
	v_mfma_f32_16x16x32_bf16 v[92:95], v[152:155], v[180:183], 0
	v_mfma_f32_16x16x32_bf16 v[104:107], v[144:147], v[188:191], 0
	v_mfma_f32_16x16x32_bf16 v[120:123], v[144:147], v[196:199], 0
	v_mfma_f32_16x16x32_bf16 v[88:91], v[148:151], v[184:187], v[88:91]
	v_mfma_f32_16x16x32_bf16 v[92:95], v[156:159], v[184:187], v[92:95]
	v_mfma_f32_16x16x32_bf16 v[104:107], v[148:151], v[192:195], v[104:107]
	v_mfma_f32_16x16x32_bf16 v[108:111], v[152:155], v[188:191], 0
	v_mfma_f32_16x16x32_bf16 v[120:123], v[148:151], v[228:231], v[120:123]
	v_mfma_f32_16x16x32_bf16 v[124:127], v[152:155], v[196:199], 0
	v_mfma_f32_16x16x32_bf16 v[108:111], v[156:159], v[192:195], v[108:111]
	v_mfma_f32_16x16x32_bf16 v[124:127], v[156:159], v[228:231], v[124:127]
	s_setprio 0
	s_barrier
	s_add_i32 s54, 0, 0x18000
	s_add_i32 s60, 0, 0x1c000
	v_add_u32_e32 v245, s54, v174
	v_add_u32_e32 v244, s60, v174
	ds_read_b128 v[128:131], v245
	ds_read_b128 v[132:135], v245 offset:1024
	ds_read_b128 v[136:139], v245 offset:2048
	ds_read_b128 v[140:143], v245 offset:3072
	ds_read_b128 v[144:147], v244
	ds_read_b128 v[148:151], v244 offset:1024
	ds_read_b128 v[152:155], v244 offset:2048
	ds_read_b128 v[156:159], v244 offset:3072
	s_add_u32 s56, s22, 0x40100
	s_addc_u32 s57, s23, 0
	s_mov_b32 m0, s41
	v_lshl_add_u64 v[236:237], s[56:57], 0, v[160:161]
	ds_read_b128 v[168:171], v175 offset:32768
	ds_read_b128 v[176:179], v175 offset:33792
	ds_read_b128 v[180:183], v175 offset:34816
	ds_read_b128 v[184:187], v175 offset:35840
	ds_read_b128 v[188:191], v175 offset:36864
	ds_read_b128 v[192:195], v175 offset:37888
	ds_read_b128 v[196:199], v175 offset:38912
	ds_read_b128 v[228:231], v175 offset:39936
	global_load_lds_dwordx4 v[236:237], off
	v_lshl_add_u64 v[236:237], s[56:57], 0, v[162:163]
	s_mov_b32 m0, s42
	s_nop 0
	global_load_lds_dwordx4 v[236:237], off
	s_waitcnt vmcnt(8)
	s_waitcnt lgkmcnt(0)
	s_barrier
	s_setprio 1
	s_waitcnt lgkmcnt(0)
	v_mfma_f32_16x16x32_bf16 v[0:3], v[128:131], v[168:171], v[0:3]
	v_mfma_f32_16x16x32_bf16 v[4:7], v[136:139], v[168:171], v[4:7]
	v_mfma_f32_16x16x32_bf16 v[16:19], v[128:131], v[180:183], v[16:19]
	v_mfma_f32_16x16x32_bf16 v[20:23], v[136:139], v[180:183], v[20:23]
	v_mfma_f32_16x16x32_bf16 v[32:35], v[128:131], v[188:191], v[32:35]
	v_mfma_f32_16x16x32_bf16 v[36:39], v[136:139], v[188:191], v[36:39]
	v_mfma_f32_16x16x32_bf16 v[48:51], v[128:131], v[196:199], v[48:51]
	v_mfma_f32_16x16x32_bf16 v[52:55], v[136:139], v[196:199], v[52:55]
	v_mfma_f32_16x16x32_bf16 v[0:3], v[132:135], v[176:179], v[0:3]
	v_mfma_f32_16x16x32_bf16 v[4:7], v[140:143], v[176:179], v[4:7]
	v_mfma_f32_16x16x32_bf16 v[16:19], v[132:135], v[184:187], v[16:19]
	v_mfma_f32_16x16x32_bf16 v[20:23], v[140:143], v[184:187], v[20:23]
	v_mfma_f32_16x16x32_bf16 v[32:35], v[132:135], v[192:195], v[32:35]
	v_mfma_f32_16x16x32_bf16 v[36:39], v[140:143], v[192:195], v[36:39]
	v_mfma_f32_16x16x32_bf16 v[48:51], v[132:135], v[228:231], v[48:51]
	v_mfma_f32_16x16x32_bf16 v[52:55], v[140:143], v[228:231], v[52:55]
	s_setprio 0
	s_setprio 1
	v_mfma_f32_16x16x32_bf16 v[8:11], v[144:147], v[168:171], v[8:11]
	v_mfma_f32_16x16x32_bf16 v[24:27], v[144:147], v[180:183], v[24:27]
	v_mfma_f32_16x16x32_bf16 v[28:31], v[152:155], v[180:183], v[28:31]
	v_mfma_f32_16x16x32_bf16 v[44:47], v[152:155], v[188:191], v[44:47]
	v_mfma_f32_16x16x32_bf16 v[56:59], v[144:147], v[196:199], v[56:59]
	v_mfma_f32_16x16x32_bf16 v[60:63], v[152:155], v[196:199], v[60:63]
	v_mfma_f32_16x16x32_bf16 v[8:11], v[148:151], v[176:179], v[8:11]
	v_mfma_f32_16x16x32_bf16 v[12:15], v[152:155], v[168:171], v[12:15]
	v_mfma_f32_16x16x32_bf16 v[24:27], v[148:151], v[184:187], v[24:27]
	v_mfma_f32_16x16x32_bf16 v[28:31], v[156:159], v[184:187], v[28:31]
	v_mfma_f32_16x16x32_bf16 v[40:43], v[144:147], v[188:191], v[40:43]
	v_mfma_f32_16x16x32_bf16 v[44:47], v[156:159], v[192:195], v[44:47]
	v_mfma_f32_16x16x32_bf16 v[56:59], v[148:151], v[228:231], v[56:59]
	v_mfma_f32_16x16x32_bf16 v[60:63], v[156:159], v[228:231], v[60:63]
	v_mfma_f32_16x16x32_bf16 v[12:15], v[156:159], v[176:179], v[12:15]
	v_mfma_f32_16x16x32_bf16 v[40:43], v[148:151], v[192:195], v[40:43]
	s_setprio 0
	s_barrier
	s_add_i32 s56, s54, s38
	s_mov_b64 s[62:63], 0x180
	s_add_i32 s54, s56, 0x2000
	v_lshl_add_u64 v[236:237], v[246:247], 0, s[62:63]
	s_mov_b32 m0, s56
	s_add_u32 s58, s24, 0x10180
	ds_read_b128 v[168:171], v175 offset:49152
	ds_read_b128 v[176:179], v175 offset:50176
	ds_read_b128 v[180:183], v175 offset:51200
	ds_read_b128 v[184:187], v175 offset:52224
	ds_read_b128 v[188:191], v175 offset:53248
	ds_read_b128 v[192:195], v175 offset:54272
	ds_read_b128 v[196:199], v175 offset:55296
	ds_read_b128 v[228:231], v175 offset:56320
	global_load_lds_dwordx4 v[236:237], off
	v_lshl_add_u64 v[246:247], v[242:243], 0, s[62:63]
	s_mov_b32 m0, s54
	s_addc_u32 s59, s25, 0
	s_add_i32 s24, s60, s38
	global_load_lds_dwordx4 v[246:247], off
	v_lshl_add_u64 v[246:247], s[58:59], 0, v[232:233]
	s_mov_b32 m0, s24
	s_add_i32 s25, s24, 0x2000
	global_load_lds_dwordx4 v[246:247], off
	v_lshl_add_u64 v[246:247], s[58:59], 0, v[164:165]
	s_mov_b32 m0, s25
	s_nop 0
	global_load_lds_dwordx4 v[246:247], off
	v_lshl_add_u64 v[246:247], v[240:241], 0, s[62:63]
	s_mov_b32 m0, s47
	s_nop 0
	global_load_lds_dwordx4 v[246:247], off
	v_lshl_add_u64 v[246:247], v[238:239], 0, s[62:63]
	s_mov_b32 m0, s48
	s_nop 0
	global_load_lds_dwordx4 v[246:247], off
	s_waitcnt vmcnt(8)
	s_waitcnt lgkmcnt(0)
	s_barrier
	s_setprio 1
	s_waitcnt lgkmcnt(0)
	v_mfma_f32_16x16x32_bf16 v[64:67], v[128:131], v[168:171], v[64:67]
	v_mfma_f32_16x16x32_bf16 v[68:71], v[136:139], v[168:171], v[68:71]
	v_mfma_f32_16x16x32_bf16 v[84:87], v[136:139], v[180:183], v[84:87]
	v_mfma_f32_16x16x32_bf16 v[96:99], v[128:131], v[188:191], v[96:99]
	v_mfma_f32_16x16x32_bf16 v[112:115], v[128:131], v[196:199], v[112:115]
	v_mfma_f32_16x16x32_bf16 v[116:119], v[136:139], v[196:199], v[116:119]
	v_mfma_f32_16x16x32_bf16 v[64:67], v[132:135], v[176:179], v[64:67]
	v_mfma_f32_16x16x32_bf16 v[68:71], v[140:143], v[176:179], v[68:71]
	v_mfma_f32_16x16x32_bf16 v[80:83], v[128:131], v[180:183], v[80:83]
	v_mfma_f32_16x16x32_bf16 v[84:87], v[140:143], v[184:187], v[84:87]
	v_mfma_f32_16x16x32_bf16 v[96:99], v[132:135], v[192:195], v[96:99]
	v_mfma_f32_16x16x32_bf16 v[100:103], v[136:139], v[188:191], v[100:103]
	v_mfma_f32_16x16x32_bf16 v[112:115], v[132:135], v[228:231], v[112:115]
	v_mfma_f32_16x16x32_bf16 v[116:119], v[140:143], v[228:231], v[116:119]
	v_mfma_f32_16x16x32_bf16 v[80:83], v[132:135], v[184:187], v[80:83]
	v_mfma_f32_16x16x32_bf16 v[100:103], v[140:143], v[192:195], v[100:103]
	s_setprio 0
	s_setprio 1
	v_mfma_f32_16x16x32_bf16 v[72:75], v[144:147], v[168:171], v[72:75]
	v_mfma_f32_16x16x32_bf16 v[76:79], v[152:155], v[168:171], v[76:79]
	v_mfma_f32_16x16x32_bf16 v[88:91], v[144:147], v[180:183], v[88:91]
	v_mfma_f32_16x16x32_bf16 v[92:95], v[152:155], v[180:183], v[92:95]
	v_mfma_f32_16x16x32_bf16 v[104:107], v[144:147], v[188:191], v[104:107]
	v_mfma_f32_16x16x32_bf16 v[108:111], v[152:155], v[188:191], v[108:111]
	v_mfma_f32_16x16x32_bf16 v[124:127], v[152:155], v[196:199], v[124:127]
	v_mfma_f32_16x16x32_bf16 v[72:75], v[148:151], v[176:179], v[72:75]
	v_mfma_f32_16x16x32_bf16 v[76:79], v[156:159], v[176:179], v[76:79]
	v_mfma_f32_16x16x32_bf16 v[92:95], v[156:159], v[184:187], v[92:95]
	v_mfma_f32_16x16x32_bf16 v[104:107], v[148:151], v[192:195], v[104:107]
	v_mfma_f32_16x16x32_bf16 v[108:111], v[156:159], v[192:195], v[108:111]
	v_mfma_f32_16x16x32_bf16 v[120:123], v[144:147], v[196:199], v[120:123]
	v_mfma_f32_16x16x32_bf16 v[124:127], v[156:159], v[228:231], v[124:127]
	v_mfma_f32_16x16x32_bf16 v[88:91], v[148:151], v[184:187], v[88:91]
	v_mfma_f32_16x16x32_bf16 v[120:123], v[148:151], v[228:231], v[120:123]
	s_setprio 0
	s_barrier
	ds_read_b128 v[128:131], v253
	ds_read_b128 v[132:135], v253 offset:1024
	ds_read_b128 v[136:139], v253 offset:2048
	ds_read_b128 v[140:143], v253 offset:3072
	ds_read_b128 v[144:147], v252
	ds_read_b128 v[148:151], v252 offset:1024
	ds_read_b128 v[152:155], v252 offset:2048
	ds_read_b128 v[156:159], v252 offset:3072
	s_add_u32 s22, s22, 0x40180
	s_addc_u32 s23, s23, 0
	s_mov_b32 m0, s55
	v_lshl_add_u64 v[252:253], s[22:23], 0, v[160:161]
	ds_read_b128 v[168:171], v175
	ds_read_b128 v[176:179], v175 offset:1024
	ds_read_b128 v[180:183], v175 offset:2048
	ds_read_b128 v[184:187], v175 offset:3072
	ds_read_b128 v[188:191], v175 offset:4096
	ds_read_b128 v[192:195], v175 offset:5120
	ds_read_b128 v[196:199], v175 offset:6144
	ds_read_b128 v[228:231], v175 offset:7168
	global_load_lds_dwordx4 v[252:253], off
	v_lshl_add_u64 v[252:253], s[22:23], 0, v[162:163]
	s_mov_b32 m0, s13
	s_nop 0
	global_load_lds_dwordx4 v[252:253], off
	s_waitcnt vmcnt(8)
	s_waitcnt lgkmcnt(0)
	s_barrier
	s_setprio 1
	s_waitcnt lgkmcnt(0)
	v_mfma_f32_16x16x32_bf16 v[0:3], v[128:131], v[168:171], v[0:3]
	v_mfma_f32_16x16x32_bf16 v[4:7], v[136:139], v[168:171], v[4:7]
	v_mfma_f32_16x16x32_bf16 v[16:19], v[128:131], v[180:183], v[16:19]
	v_mfma_f32_16x16x32_bf16 v[20:23], v[136:139], v[180:183], v[20:23]
	v_mfma_f32_16x16x32_bf16 v[32:35], v[128:131], v[188:191], v[32:35]
	v_mfma_f32_16x16x32_bf16 v[36:39], v[136:139], v[188:191], v[36:39]
	v_mfma_f32_16x16x32_bf16 v[48:51], v[128:131], v[196:199], v[48:51]
	v_mfma_f32_16x16x32_bf16 v[0:3], v[132:135], v[176:179], v[0:3]
	v_mfma_f32_16x16x32_bf16 v[4:7], v[140:143], v[176:179], v[4:7]
	v_mfma_f32_16x16x32_bf16 v[16:19], v[132:135], v[184:187], v[16:19]
	v_mfma_f32_16x16x32_bf16 v[20:23], v[140:143], v[184:187], v[20:23]
	v_mfma_f32_16x16x32_bf16 v[32:35], v[132:135], v[192:195], v[32:35]
	v_mfma_f32_16x16x32_bf16 v[36:39], v[140:143], v[192:195], v[36:39]
	v_mfma_f32_16x16x32_bf16 v[48:51], v[132:135], v[228:231], v[48:51]
	v_mfma_f32_16x16x32_bf16 v[52:55], v[136:139], v[196:199], v[52:55]
	v_mfma_f32_16x16x32_bf16 v[52:55], v[140:143], v[228:231], v[52:55]
	s_setprio 0
	s_setprio 1
	v_mfma_f32_16x16x32_bf16 v[8:11], v[144:147], v[168:171], v[8:11]
	v_mfma_f32_16x16x32_bf16 v[24:27], v[144:147], v[180:183], v[24:27]
	v_mfma_f32_16x16x32_bf16 v[28:31], v[152:155], v[180:183], v[28:31]
	v_mfma_f32_16x16x32_bf16 v[44:47], v[152:155], v[188:191], v[44:47]
	v_mfma_f32_16x16x32_bf16 v[56:59], v[144:147], v[196:199], v[56:59]
	v_mfma_f32_16x16x32_bf16 v[60:63], v[152:155], v[196:199], v[60:63]
	v_mfma_f32_16x16x32_bf16 v[8:11], v[148:151], v[176:179], v[8:11]
	v_mfma_f32_16x16x32_bf16 v[12:15], v[152:155], v[168:171], v[12:15]
	v_mfma_f32_16x16x32_bf16 v[24:27], v[148:151], v[184:187], v[24:27]
	v_mfma_f32_16x16x32_bf16 v[28:31], v[156:159], v[184:187], v[28:31]
	v_mfma_f32_16x16x32_bf16 v[40:43], v[144:147], v[188:191], v[40:43]
	v_mfma_f32_16x16x32_bf16 v[44:47], v[156:159], v[192:195], v[44:47]
	v_mfma_f32_16x16x32_bf16 v[56:59], v[148:151], v[228:231], v[56:59]
	v_mfma_f32_16x16x32_bf16 v[60:63], v[156:159], v[228:231], v[60:63]
	v_mfma_f32_16x16x32_bf16 v[12:15], v[156:159], v[176:179], v[12:15]
	v_mfma_f32_16x16x32_bf16 v[40:43], v[148:151], v[192:195], v[40:43]
	s_setprio 0
	s_barrier
	s_mov_b32 m0, s53
	v_lshl_add_u64 v[252:253], s[26:27], 0, v[232:233]
	s_add_u32 s22, s26, 0x10000
	ds_read_b128 v[168:171], v175 offset:16384
	ds_read_b128 v[176:179], v175 offset:17408
	ds_read_b128 v[180:183], v175 offset:18432
	ds_read_b128 v[184:187], v175 offset:19456
	ds_read_b128 v[188:191], v175 offset:20480
	ds_read_b128 v[192:195], v175 offset:21504
	ds_read_b128 v[196:199], v175 offset:22528
	ds_read_b128 v[228:231], v175 offset:23552
	global_load_lds_dwordx4 v[252:253], off
	v_lshl_add_u64 v[246:247], s[26:27], 0, v[164:165]
	s_mov_b32 m0, s15
	s_addc_u32 s23, s27, 0
	global_load_lds_dwordx4 v[246:247], off
	v_lshl_add_u64 v[242:243], s[22:23], 0, v[232:233]
	s_mov_b32 m0, s21
	v_lshl_add_u64 v[240:241], s[28:29], 0, v[160:161]
	global_load_lds_dwordx4 v[242:243], off
	v_lshl_add_u64 v[242:243], s[22:23], 0, v[164:165]
	s_mov_b32 m0, s52
	v_lshl_add_u64 v[238:239], s[28:29], 0, v[162:163]
	global_load_lds_dwordx4 v[242:243], off
	s_mov_b32 m0, s39
	s_nop 0
	global_load_lds_dwordx4 v[240:241], off
	s_mov_b32 m0, s40
	s_nop 0
	global_load_lds_dwordx4 v[238:239], off
	s_waitcnt vmcnt(8)
	s_waitcnt lgkmcnt(0)
	s_barrier
	s_setprio 1
	s_waitcnt lgkmcnt(0)
	v_mfma_f32_16x16x32_bf16 v[64:67], v[128:131], v[168:171], v[64:67]
	v_mfma_f32_16x16x32_bf16 v[64:67], v[132:135], v[176:179], v[64:67]
	v_mfma_f32_16x16x32_bf16 v[68:71], v[136:139], v[168:171], v[68:71]
	v_mfma_f32_16x16x32_bf16 v[68:71], v[140:143], v[176:179], v[68:71]
	v_mfma_f32_16x16x32_bf16 v[80:83], v[128:131], v[180:183], v[80:83]
	v_mfma_f32_16x16x32_bf16 v[80:83], v[132:135], v[184:187], v[80:83]
	v_mfma_f32_16x16x32_bf16 v[84:87], v[136:139], v[180:183], v[84:87]
	v_mfma_f32_16x16x32_bf16 v[84:87], v[140:143], v[184:187], v[84:87]
	v_mfma_f32_16x16x32_bf16 v[96:99], v[128:131], v[188:191], v[96:99]
	v_mfma_f32_16x16x32_bf16 v[112:115], v[128:131], v[196:199], v[112:115]
	v_mfma_f32_16x16x32_bf16 v[116:119], v[136:139], v[196:199], v[116:119]
	v_mfma_f32_16x16x32_bf16 v[96:99], v[132:135], v[192:195], v[96:99]
	v_mfma_f32_16x16x32_bf16 v[100:103], v[136:139], v[188:191], v[100:103]
	v_mfma_f32_16x16x32_bf16 v[112:115], v[132:135], v[228:231], v[112:115]
	v_mfma_f32_16x16x32_bf16 v[116:119], v[140:143], v[228:231], v[116:119]
	v_mfma_f32_16x16x32_bf16 v[100:103], v[140:143], v[192:195], v[100:103]
	s_setprio 0
	s_setprio 1
	v_mfma_f32_16x16x32_bf16 v[72:75], v[144:147], v[168:171], v[72:75]
	v_mfma_f32_16x16x32_bf16 v[72:75], v[148:151], v[176:179], v[72:75]
	v_mfma_f32_16x16x32_bf16 v[76:79], v[152:155], v[168:171], v[76:79]
	v_mfma_f32_16x16x32_bf16 v[76:79], v[156:159], v[176:179], v[76:79]
	v_mfma_f32_16x16x32_bf16 v[88:91], v[144:147], v[180:183], v[88:91]
	v_mfma_f32_16x16x32_bf16 v[88:91], v[148:151], v[184:187], v[88:91]
	v_mfma_f32_16x16x32_bf16 v[92:95], v[152:155], v[180:183], v[92:95]
	v_mfma_f32_16x16x32_bf16 v[92:95], v[156:159], v[184:187], v[92:95]
	v_mfma_f32_16x16x32_bf16 v[104:107], v[144:147], v[188:191], v[104:107]
	v_mfma_f32_16x16x32_bf16 v[104:107], v[148:151], v[192:195], v[104:107]
	v_mfma_f32_16x16x32_bf16 v[108:111], v[152:155], v[188:191], v[108:111]
	v_mfma_f32_16x16x32_bf16 v[108:111], v[156:159], v[192:195], v[108:111]
	v_mfma_f32_16x16x32_bf16 v[120:123], v[144:147], v[196:199], v[120:123]
	v_mfma_f32_16x16x32_bf16 v[120:123], v[148:151], v[228:231], v[120:123]
	v_mfma_f32_16x16x32_bf16 v[124:127], v[152:155], v[196:199], v[124:127]
	v_mfma_f32_16x16x32_bf16 v[124:127], v[156:159], v[228:231], v[124:127]
	s_setprio 0
	s_barrier
	s_nop 4
	ds_read_b128 v[128:131], v245
	ds_read_b128 v[132:135], v245 offset:1024
	ds_read_b128 v[136:139], v245 offset:2048
	ds_read_b128 v[140:143], v245 offset:3072
	ds_read_b128 v[144:147], v244
	ds_read_b128 v[148:151], v244 offset:1024
	ds_read_b128 v[152:155], v244 offset:2048
	ds_read_b128 v[156:159], v244 offset:3072
	s_add_u32 s22, s28, 0x40000
	s_addc_u32 s23, s29, 0
	s_mov_b32 m0, s41
	v_lshl_add_u64 v[244:245], s[22:23], 0, v[160:161]
	ds_read_b128 v[168:171], v175 offset:32768
	ds_read_b128 v[176:179], v175 offset:33792
	ds_read_b128 v[180:183], v175 offset:34816
	ds_read_b128 v[184:187], v175 offset:35840
	ds_read_b128 v[188:191], v175 offset:36864
	ds_read_b128 v[192:195], v175 offset:37888
	ds_read_b128 v[196:199], v175 offset:38912
	ds_read_b128 v[228:231], v175 offset:39936
	global_load_lds_dwordx4 v[244:245], off
	v_lshl_add_u64 v[244:245], s[22:23], 0, v[162:163]
	s_mov_b32 m0, s42
	s_nop 0
	global_load_lds_dwordx4 v[244:245], off
	s_waitcnt vmcnt(8)
	s_waitcnt lgkmcnt(0)
	s_barrier
	s_setprio 1
	s_waitcnt lgkmcnt(0)
	v_mfma_f32_16x16x32_bf16 v[0:3], v[128:131], v[168:171], v[0:3]
	v_mfma_f32_16x16x32_bf16 v[0:3], v[132:135], v[176:179], v[0:3]
	v_mfma_f32_16x16x32_bf16 v[4:7], v[136:139], v[168:171], v[4:7]
	v_mfma_f32_16x16x32_bf16 v[4:7], v[140:143], v[176:179], v[4:7]
	v_mfma_f32_16x16x32_bf16 v[16:19], v[128:131], v[180:183], v[16:19]
	v_mfma_f32_16x16x32_bf16 v[16:19], v[132:135], v[184:187], v[16:19]
	v_mfma_f32_16x16x32_bf16 v[20:23], v[136:139], v[180:183], v[20:23]
	v_mfma_f32_16x16x32_bf16 v[20:23], v[140:143], v[184:187], v[20:23]
	v_mfma_f32_16x16x32_bf16 v[32:35], v[128:131], v[188:191], v[32:35]
	v_mfma_f32_16x16x32_bf16 v[32:35], v[132:135], v[192:195], v[32:35]
	v_mfma_f32_16x16x32_bf16 v[36:39], v[136:139], v[188:191], v[36:39]
	v_mfma_f32_16x16x32_bf16 v[36:39], v[140:143], v[192:195], v[36:39]
	v_mfma_f32_16x16x32_bf16 v[48:51], v[128:131], v[196:199], v[48:51]
	v_mfma_f32_16x16x32_bf16 v[48:51], v[132:135], v[228:231], v[48:51]
	v_mfma_f32_16x16x32_bf16 v[52:55], v[136:139], v[196:199], v[52:55]
	v_mfma_f32_16x16x32_bf16 v[52:55], v[140:143], v[228:231], v[52:55]
	s_setprio 0
	s_setprio 1
	v_mfma_f32_16x16x32_bf16 v[12:15], v[152:155], v[168:171], v[12:15]
	v_mfma_f32_16x16x32_bf16 v[12:15], v[156:159], v[176:179], v[12:15]
	v_mfma_f32_16x16x32_bf16 v[24:27], v[144:147], v[180:183], v[24:27]
	v_mfma_f32_16x16x32_bf16 v[24:27], v[148:151], v[184:187], v[24:27]
	v_mfma_f32_16x16x32_bf16 v[28:31], v[152:155], v[180:183], v[28:31]
	v_mfma_f32_16x16x32_bf16 v[8:11], v[144:147], v[168:171], v[8:11]
	v_mfma_f32_16x16x32_bf16 v[28:31], v[156:159], v[184:187], v[28:31]
	v_mfma_f32_16x16x32_bf16 v[40:43], v[144:147], v[188:191], v[40:43]
	v_mfma_f32_16x16x32_bf16 v[8:11], v[148:151], v[176:179], v[8:11]
	v_mfma_f32_16x16x32_bf16 v[40:43], v[148:151], v[192:195], v[40:43]
	v_mfma_f32_16x16x32_bf16 v[44:47], v[152:155], v[188:191], v[44:47]
	v_mfma_f32_16x16x32_bf16 v[44:47], v[156:159], v[192:195], v[44:47]
	v_mfma_f32_16x16x32_bf16 v[56:59], v[144:147], v[196:199], v[56:59]
	v_mfma_f32_16x16x32_bf16 v[56:59], v[148:151], v[228:231], v[56:59]
	v_mfma_f32_16x16x32_bf16 v[60:63], v[152:155], v[196:199], v[60:63]
	v_mfma_f32_16x16x32_bf16 v[60:63], v[156:159], v[228:231], v[60:63]
	s_setprio 0
	s_barrier
	s_mov_b32 m0, s56
	v_lshl_add_u64 v[244:245], v[252:253], 0, s[94:95]
	s_add_u32 s22, s26, 0x10080
	s_nop 1
	ds_read_b128 v[168:171], v175 offset:49152
	ds_read_b128 v[176:179], v175 offset:50176
	ds_read_b128 v[180:183], v175 offset:51200
	ds_read_b128 v[184:187], v175 offset:52224
	ds_read_b128 v[188:191], v175 offset:53248
	ds_read_b128 v[192:195], v175 offset:54272
	ds_read_b128 v[196:199], v175 offset:55296
	ds_read_b128 v[228:231], v175 offset:56320
	global_load_lds_dwordx4 v[244:245], off
	v_lshl_add_u64 v[252:253], v[246:247], 0, s[94:95]
	s_mov_b32 m0, s54
	s_addc_u32 s23, s27, 0
	global_load_lds_dwordx4 v[252:253], off
	v_lshl_add_u64 v[252:253], s[22:23], 0, v[232:233]
	s_mov_b32 m0, s24
	s_nop 0
	global_load_lds_dwordx4 v[252:253], off
	v_lshl_add_u64 v[252:253], s[22:23], 0, v[164:165]
	s_mov_b32 m0, s25
	s_nop 0
	global_load_lds_dwordx4 v[252:253], off
	v_lshl_add_u64 v[252:253], v[240:241], 0, s[94:95]
	s_mov_b32 m0, s47
	s_nop 0
	global_load_lds_dwordx4 v[252:253], off
	v_lshl_add_u64 v[252:253], v[238:239], 0, s[94:95]
	s_mov_b32 m0, s48
	s_nop 0
	global_load_lds_dwordx4 v[252:253], off
	s_waitcnt vmcnt(8)
	s_waitcnt lgkmcnt(0)
	s_barrier
	s_setprio 1
	s_waitcnt lgkmcnt(0)
	v_mfma_f32_16x16x32_bf16 v[64:67], v[128:131], v[168:171], v[64:67]
	v_mfma_f32_16x16x32_bf16 v[64:67], v[132:135], v[176:179], v[64:67]
	v_mfma_f32_16x16x32_bf16 v[68:71], v[136:139], v[168:171], v[68:71]
	v_mfma_f32_16x16x32_bf16 v[68:71], v[140:143], v[176:179], v[68:71]
	v_mfma_f32_16x16x32_bf16 v[80:83], v[128:131], v[180:183], v[80:83]
	v_mfma_f32_16x16x32_bf16 v[80:83], v[132:135], v[184:187], v[80:83]
	v_mfma_f32_16x16x32_bf16 v[84:87], v[136:139], v[180:183], v[84:87]
	v_mfma_f32_16x16x32_bf16 v[84:87], v[140:143], v[184:187], v[84:87]
	v_mfma_f32_16x16x32_bf16 v[96:99], v[128:131], v[188:191], v[96:99]
	v_mfma_f32_16x16x32_bf16 v[112:115], v[128:131], v[196:199], v[112:115]
	v_mfma_f32_16x16x32_bf16 v[96:99], v[132:135], v[192:195], v[96:99]
	v_mfma_f32_16x16x32_bf16 v[100:103], v[136:139], v[188:191], v[100:103]
	v_mfma_f32_16x16x32_bf16 v[112:115], v[132:135], v[228:231], v[112:115]
	v_mfma_f32_16x16x32_bf16 v[116:119], v[136:139], v[196:199], v[116:119]
	v_mfma_f32_16x16x32_bf16 v[100:103], v[140:143], v[192:195], v[100:103]
	v_mfma_f32_16x16x32_bf16 v[116:119], v[140:143], v[228:231], v[116:119]
	s_setprio 0
	s_setprio 1
	v_mfma_f32_16x16x32_bf16 v[72:75], v[144:147], v[168:171], v[72:75]
	v_mfma_f32_16x16x32_bf16 v[72:75], v[148:151], v[176:179], v[72:75]
	v_mfma_f32_16x16x32_bf16 v[76:79], v[152:155], v[168:171], v[76:79]
	v_mfma_f32_16x16x32_bf16 v[76:79], v[156:159], v[176:179], v[76:79]
	v_mfma_f32_16x16x32_bf16 v[88:91], v[144:147], v[180:183], v[88:91]
	v_mfma_f32_16x16x32_bf16 v[88:91], v[148:151], v[184:187], v[88:91]
	v_mfma_f32_16x16x32_bf16 v[92:95], v[152:155], v[180:183], v[92:95]
	v_mfma_f32_16x16x32_bf16 v[92:95], v[156:159], v[184:187], v[92:95]
	v_mfma_f32_16x16x32_bf16 v[104:107], v[144:147], v[188:191], v[104:107]
	v_mfma_f32_16x16x32_bf16 v[104:107], v[148:151], v[192:195], v[104:107]
	v_mfma_f32_16x16x32_bf16 v[108:111], v[152:155], v[188:191], v[108:111]
	v_mfma_f32_16x16x32_bf16 v[108:111], v[156:159], v[192:195], v[108:111]
	v_mfma_f32_16x16x32_bf16 v[120:123], v[144:147], v[196:199], v[120:123]
	v_mfma_f32_16x16x32_bf16 v[120:123], v[148:151], v[228:231], v[120:123]
	v_mfma_f32_16x16x32_bf16 v[124:127], v[152:155], v[196:199], v[124:127]
	v_mfma_f32_16x16x32_bf16 v[124:127], v[156:159], v[228:231], v[124:127]
	s_setprio 0
	s_barrier
	s_andn2_b64 vcc, exec, s[10:11]
	s_cbranch_vccnz .LBB0_1020
	s_barrier
.LBB0_1020:
	s_lshl_b32 s13, s20, 8
	s_lshl_b32 s20, s5, 10
	v_mbcnt_lo_u32_b32 v236, -1, 0
	v_mbcnt_hi_u32_b32 v236, -1, v236
	s_lshl_b32 s4, s4, 8
	v_and_or_b32 v176, v236, 15, s45
	s_ashr_i32 s21, s20, 31
	v_ashrrev_i32_e32 v236, 1, v236
	v_add_u32_e32 v168, s13, v176
	s_or_b32 s4, s4, s46
	s_lshl_b64 s[20:21], s[20:21], 1
	v_and_b32_e32 v236, -8, v236
	s_add_u32 s20, s43, s20
	v_ashrrev_i32_e32 v169, 31, v168
	v_add_u32_e32 v166, s4, v236
	s_addc_u32 s21, s44, s21
	v_lshlrev_b64 v[236:237], 13, v[168:169]
	v_lshl_add_u64 v[236:237], s[20:21], 0, v[236:237]
	v_ashrrev_i32_e32 v167, 31, v166
	v_lshl_add_u64 v[236:237], v[166:167], 1, v[236:237]
	v_lshlrev_b64 v[238:239], 11, v[168:169]
	v_lshl_add_u64 v[238:239], s[8:9], 0, v[238:239]
	v_lshl_add_u64 v[172:173], v[166:167], 1, v[238:239]
	v_mov_b64_e32 v[170:171], v[236:237]
	v_mov_b64_e32 v[230:231], v[250:251]
	v_mov_b32_e32 v243, v249
	v_mov_b32_e32 v251, v248
	v_mov_b32_e32 v249, 0x358637bd
	v_mov_b32_e32 v248, 0x260
	s_mov_b32 s59, 0
	s_waitcnt lgkmcnt(0)
	s_cmp_eq_u32 s5, 0
	s_cbranch_scc1 .Lmepi_z0
	s_cmp_eq_u32 s5, 3
	s_cbranch_scc1 .Lmepi_z3
	global_load_dwordx4 v[128:131], v[170:171], off nt
	global_load_dwordx4 v[132:135], v[170:171], off offset:256 nt
	s_mov_b32 s58, 0x20000
	v_lshl_add_u64 v[244:245], v[170:171], 0, s[58:59]
	global_load_dwordx4 v[136:139], v[244:245], off nt
	global_load_dwordx4 v[140:143], v[244:245], off offset:256 nt
	s_mov_b32 s58, 0x40000
	v_lshl_add_u64 v[246:247], v[170:171], 0, s[58:59]
	global_load_dwordx4 v[144:147], v[246:247], off nt
	global_load_dwordx4 v[148:151], v[246:247], off offset:256 nt
	s_mov_b32 s58, 0x60000
	v_lshl_add_u64 v[252:253], v[170:171], 0, s[58:59]
	global_load_dwordx4 v[152:155], v[252:253], off nt
	global_load_dwordx4 v[156:159], v[252:253], off offset:256 nt
	s_mov_b32 s58, 0x18000
	v_lshl_add_u64 v[178:179], v[172:173], 0, s[58:59]
	global_load_dwordx4 v[180:183], v[178:179], off offset:256
	s_mov_b32 s58, 0x100000
	v_lshl_add_u64 v[240:241], v[170:171], 0, s[58:59]
	global_load_dwordx4 v[184:187], v[240:241], off nt
	global_load_dwordx4 v[188:191], v[240:241], off offset:256 nt
	s_mov_b32 s58, 0x40000
	v_lshl_add_u64 v[244:245], v[172:173], 0, s[58:59]
	global_load_dwordx4 v[192:195], v[244:245], off
	global_load_dwordx4 v[196:199], v[244:245], off offset:256
	s_waitcnt vmcnt(12)
	v_lshlrev_b32_e32 v246, 16, v128
	v_and_b32_e32 v247, 0xffff0000, v128
	v_pk_mul_f32 v[0:1], v[0:1], v[246:247]
	v_lshlrev_b32_e32 v252, 16, v129
	v_and_b32_e32 v253, 0xffff0000, v129
	v_pk_mul_f32 v[2:3], v[2:3], v[252:253]
	v_lshlrev_b32_e32 v178, 16, v130
	v_and_b32_e32 v179, 0xffff0000, v130
	v_pk_mul_f32 v[4:5], v[4:5], v[178:179]
	v_lshlrev_b32_e32 v240, 16, v131
	v_and_b32_e32 v241, 0xffff0000, v131
	v_pk_mul_f32 v[6:7], v[6:7], v[240:241]
	v_lshlrev_b32_e32 v244, 16, v200
	v_and_b32_e32 v245, 0xffff0000, v200
	v_pk_add_f32 v[0:1], v[0:1], v[244:245]
	v_lshlrev_b32_e32 v246, 16, v201
	v_and_b32_e32 v247, 0xffff0000, v201
	v_pk_add_f32 v[2:3], v[2:3], v[246:247]
	v_lshlrev_b32_e32 v252, 16, v202
	v_and_b32_e32 v253, 0xffff0000, v202
	v_pk_add_f32 v[4:5], v[4:5], v[252:253]
	v_lshlrev_b32_e32 v178, 16, v203
	v_and_b32_e32 v179, 0xffff0000, v203
	v_pk_add_f32 v[6:7], v[6:7], v[178:179]
	v_cvt_pk_bf16_f32 v200, v0, v1
	v_cvt_pk_bf16_f32 v201, v2, v3
	v_cvt_pk_bf16_f32 v202, v4, v5
	v_cvt_pk_bf16_f32 v203, v6, v7
	s_waitcnt vmcnt(11)
	v_lshlrev_b32_e32 v240, 16, v132
	v_and_b32_e32 v241, 0xffff0000, v132
	v_pk_mul_f32 v[8:9], v[8:9], v[240:241]
	v_lshlrev_b32_e32 v244, 16, v133
	v_and_b32_e32 v245, 0xffff0000, v133
	v_pk_mul_f32 v[10:11], v[10:11], v[244:245]
	v_lshlrev_b32_e32 v246, 16, v134
	v_and_b32_e32 v247, 0xffff0000, v134
	v_pk_mul_f32 v[12:13], v[12:13], v[246:247]
	v_lshlrev_b32_e32 v252, 16, v135
	v_and_b32_e32 v253, 0xffff0000, v135
	v_pk_mul_f32 v[14:15], v[14:15], v[252:253]
	v_lshlrev_b32_e32 v178, 16, v204
	v_and_b32_e32 v179, 0xffff0000, v204
	v_pk_add_f32 v[8:9], v[8:9], v[178:179]
	v_lshlrev_b32_e32 v240, 16, v205
	v_and_b32_e32 v241, 0xffff0000, v205
	v_pk_add_f32 v[10:11], v[10:11], v[240:241]
	v_lshlrev_b32_e32 v244, 16, v206
	v_and_b32_e32 v245, 0xffff0000, v206
	v_pk_add_f32 v[12:13], v[12:13], v[244:245]
	v_lshlrev_b32_e32 v246, 16, v207
	v_and_b32_e32 v247, 0xffff0000, v207
	v_pk_add_f32 v[14:15], v[14:15], v[246:247]
	v_cvt_pk_bf16_f32 v204, v8, v9
	v_cvt_pk_bf16_f32 v205, v10, v11
	v_cvt_pk_bf16_f32 v206, v12, v13
	v_cvt_pk_bf16_f32 v207, v14, v15
	s_mov_b32 s58, 0x120000
	v_lshl_add_u64 v[252:253], v[170:171], 0, s[58:59]
	global_load_dwordx4 v[236:239], v[252:253], off nt
	global_load_dwordx4 v[0:3], v[252:253], off offset:256 nt
	s_mov_b32 s58, 0x48000
	v_lshl_add_u64 v[178:179], v[172:173], 0, s[58:59]
	global_load_dwordx4 v[4:7], v[178:179], off
	global_load_dwordx4 v[128:131], v[178:179], off offset:256
	s_waitcnt vmcnt(14)
	v_lshlrev_b32_e32 v240, 16, v136
	v_and_b32_e32 v241, 0xffff0000, v136
	v_pk_mul_f32 v[16:17], v[16:17], v[240:241]
	v_lshlrev_b32_e32 v244, 16, v137
	v_and_b32_e32 v245, 0xffff0000, v137
	v_pk_mul_f32 v[18:19], v[18:19], v[244:245]
	v_lshlrev_b32_e32 v246, 16, v138
	v_and_b32_e32 v247, 0xffff0000, v138
	v_pk_mul_f32 v[20:21], v[20:21], v[246:247]
	v_lshlrev_b32_e32 v252, 16, v139
	v_and_b32_e32 v253, 0xffff0000, v139
	v_pk_mul_f32 v[22:23], v[22:23], v[252:253]
	v_lshlrev_b32_e32 v178, 16, v208
	v_and_b32_e32 v179, 0xffff0000, v208
	v_pk_add_f32 v[16:17], v[16:17], v[178:179]
	v_lshlrev_b32_e32 v240, 16, v209
	v_and_b32_e32 v241, 0xffff0000, v209
	v_pk_add_f32 v[18:19], v[18:19], v[240:241]
	v_lshlrev_b32_e32 v244, 16, v210
	v_and_b32_e32 v245, 0xffff0000, v210
	v_pk_add_f32 v[20:21], v[20:21], v[244:245]
	v_lshlrev_b32_e32 v246, 16, v211
	v_and_b32_e32 v247, 0xffff0000, v211
	v_pk_add_f32 v[22:23], v[22:23], v[246:247]
	v_cvt_pk_bf16_f32 v208, v16, v17
	v_cvt_pk_bf16_f32 v209, v18, v19
	v_cvt_pk_bf16_f32 v210, v20, v21
	v_cvt_pk_bf16_f32 v211, v22, v23
	s_waitcnt vmcnt(13)
	v_lshlrev_b32_e32 v252, 16, v140
	v_and_b32_e32 v253, 0xffff0000, v140
	v_pk_mul_f32 v[24:25], v[24:25], v[252:253]
	v_lshlrev_b32_e32 v178, 16, v141
	v_and_b32_e32 v179, 0xffff0000, v141
	v_pk_mul_f32 v[26:27], v[26:27], v[178:179]
	v_lshlrev_b32_e32 v240, 16, v142
	v_and_b32_e32 v241, 0xffff0000, v142
	v_pk_mul_f32 v[28:29], v[28:29], v[240:241]
	v_lshlrev_b32_e32 v244, 16, v143
	v_and_b32_e32 v245, 0xffff0000, v143
	v_pk_mul_f32 v[30:31], v[30:31], v[244:245]
	v_lshlrev_b32_e32 v246, 16, v212
	v_and_b32_e32 v247, 0xffff0000, v212
	v_pk_add_f32 v[24:25], v[24:25], v[246:247]
	v_lshlrev_b32_e32 v252, 16, v213
	v_and_b32_e32 v253, 0xffff0000, v213
	v_pk_add_f32 v[26:27], v[26:27], v[252:253]
	v_lshlrev_b32_e32 v178, 16, v214
	v_and_b32_e32 v179, 0xffff0000, v214
	v_pk_add_f32 v[28:29], v[28:29], v[178:179]
	v_lshlrev_b32_e32 v240, 16, v215
	v_and_b32_e32 v241, 0xffff0000, v215
	v_pk_add_f32 v[30:31], v[30:31], v[240:241]
	v_cvt_pk_bf16_f32 v212, v24, v25
	v_cvt_pk_bf16_f32 v213, v26, v27
	v_cvt_pk_bf16_f32 v214, v28, v29
	v_cvt_pk_bf16_f32 v215, v30, v31
	s_mov_b32 s58, 0x140000
	v_lshl_add_u64 v[244:245], v[170:171], 0, s[58:59]
	global_load_dwordx4 v[8:11], v[244:245], off nt
	global_load_dwordx4 v[12:15], v[244:245], off offset:256 nt
	s_mov_b32 s58, 0x50000
	v_lshl_add_u64 v[246:247], v[172:173], 0, s[58:59]
	global_load_dwordx4 v[132:135], v[246:247], off
	global_load_dwordx4 v[16:19], v[246:247], off offset:256
	s_mov_b32 s58, 0x160000
	v_lshl_add_u64 v[252:253], v[170:171], 0, s[58:59]
	global_load_dwordx4 v[20:23], v[252:253], off nt
	global_load_dwordx4 v[136:139], v[252:253], off offset:256 nt
	s_mov_b32 s58, 0x58000
	v_lshl_add_u64 v[178:179], v[172:173], 0, s[58:59]
	global_load_dwordx4 v[24:27], v[178:179], off
	global_load_dwordx4 v[28:31], v[178:179], off offset:256
	s_waitcnt vmcnt(20)
	v_lshlrev_b32_e32 v240, 16, v144
	v_and_b32_e32 v241, 0xffff0000, v144
	v_pk_mul_f32 v[32:33], v[32:33], v[240:241]
	v_lshlrev_b32_e32 v244, 16, v145
	v_and_b32_e32 v245, 0xffff0000, v145
	v_pk_mul_f32 v[34:35], v[34:35], v[244:245]
	v_lshlrev_b32_e32 v246, 16, v146
	v_and_b32_e32 v247, 0xffff0000, v146
	v_pk_mul_f32 v[36:37], v[36:37], v[246:247]
	v_lshlrev_b32_e32 v252, 16, v147
	v_and_b32_e32 v253, 0xffff0000, v147
	v_pk_mul_f32 v[38:39], v[38:39], v[252:253]
	v_lshlrev_b32_e32 v178, 16, v216
	v_and_b32_e32 v179, 0xffff0000, v216
	v_pk_add_f32 v[32:33], v[32:33], v[178:179]
	v_lshlrev_b32_e32 v240, 16, v217
	v_and_b32_e32 v241, 0xffff0000, v217
	v_pk_add_f32 v[34:35], v[34:35], v[240:241]
	v_lshlrev_b32_e32 v244, 16, v218
	v_and_b32_e32 v245, 0xffff0000, v218
	v_pk_add_f32 v[36:37], v[36:37], v[244:245]
	v_lshlrev_b32_e32 v246, 16, v219
	v_and_b32_e32 v247, 0xffff0000, v219
	v_pk_add_f32 v[38:39], v[38:39], v[246:247]
	v_cvt_pk_bf16_f32 v216, v32, v33
	v_cvt_pk_bf16_f32 v217, v34, v35
	v_cvt_pk_bf16_f32 v218, v36, v37
	v_cvt_pk_bf16_f32 v219, v38, v39
	s_waitcnt vmcnt(19)
	v_lshlrev_b32_e32 v252, 16, v148
	v_and_b32_e32 v253, 0xffff0000, v148
	v_pk_mul_f32 v[40:41], v[40:41], v[252:253]
	v_lshlrev_b32_e32 v178, 16, v149
	v_and_b32_e32 v179, 0xffff0000, v149
	v_pk_mul_f32 v[42:43], v[42:43], v[178:179]
	v_lshlrev_b32_e32 v240, 16, v150
	v_and_b32_e32 v241, 0xffff0000, v150
	v_pk_mul_f32 v[44:45], v[44:45], v[240:241]
	v_lshlrev_b32_e32 v244, 16, v151
	v_and_b32_e32 v245, 0xffff0000, v151
	v_pk_mul_f32 v[46:47], v[46:47], v[244:245]
	v_lshlrev_b32_e32 v246, 16, v220
	v_and_b32_e32 v247, 0xffff0000, v220
	v_pk_add_f32 v[40:41], v[40:41], v[246:247]
	v_lshlrev_b32_e32 v252, 16, v221
	v_and_b32_e32 v253, 0xffff0000, v221
	v_pk_add_f32 v[42:43], v[42:43], v[252:253]
	v_lshlrev_b32_e32 v178, 16, v222
	v_and_b32_e32 v179, 0xffff0000, v222
	v_pk_add_f32 v[44:45], v[44:45], v[178:179]
	v_lshlrev_b32_e32 v240, 16, v223
	v_and_b32_e32 v241, 0xffff0000, v223
	v_pk_add_f32 v[46:47], v[46:47], v[240:241]
	v_cvt_pk_bf16_f32 v220, v40, v41
	v_cvt_pk_bf16_f32 v221, v42, v43
	v_cvt_pk_bf16_f32 v222, v44, v45
	v_cvt_pk_bf16_f32 v223, v46, v47
	s_waitcnt vmcnt(18)
	v_lshlrev_b32_e32 v244, 16, v152
	v_and_b32_e32 v245, 0xffff0000, v152
	v_pk_mul_f32 v[48:49], v[48:49], v[244:245]
	v_lshlrev_b32_e32 v246, 16, v153
	v_and_b32_e32 v247, 0xffff0000, v153
	v_pk_mul_f32 v[50:51], v[50:51], v[246:247]
	v_lshlrev_b32_e32 v252, 16, v154
	v_and_b32_e32 v253, 0xffff0000, v154
	v_pk_mul_f32 v[52:53], v[52:53], v[252:253]
	v_lshlrev_b32_e32 v178, 16, v155
	v_and_b32_e32 v179, 0xffff0000, v155
	v_pk_mul_f32 v[54:55], v[54:55], v[178:179]
	v_lshlrev_b32_e32 v240, 16, v224
	v_and_b32_e32 v241, 0xffff0000, v224
	v_pk_add_f32 v[48:49], v[48:49], v[240:241]
	v_lshlrev_b32_e32 v244, 16, v225
	v_and_b32_e32 v245, 0xffff0000, v225
	v_pk_add_f32 v[50:51], v[50:51], v[244:245]
	v_lshlrev_b32_e32 v246, 16, v226
	v_and_b32_e32 v247, 0xffff0000, v226
	v_pk_add_f32 v[52:53], v[52:53], v[246:247]
	v_lshlrev_b32_e32 v252, 16, v227
	v_and_b32_e32 v253, 0xffff0000, v227
	v_pk_add_f32 v[54:55], v[54:55], v[252:253]
	v_cvt_pk_bf16_f32 v224, v48, v49
	v_cvt_pk_bf16_f32 v225, v50, v51
	v_cvt_pk_bf16_f32 v226, v52, v53
	v_cvt_pk_bf16_f32 v227, v54, v55
	s_waitcnt vmcnt(16)
	v_lshlrev_b32_e32 v178, 16, v156
	v_and_b32_e32 v179, 0xffff0000, v156
	v_pk_mul_f32 v[56:57], v[56:57], v[178:179]
	v_lshlrev_b32_e32 v240, 16, v157
	v_and_b32_e32 v241, 0xffff0000, v157
	v_pk_mul_f32 v[58:59], v[58:59], v[240:241]
	v_lshlrev_b32_e32 v244, 16, v158
	v_and_b32_e32 v245, 0xffff0000, v158
	v_pk_mul_f32 v[60:61], v[60:61], v[244:245]
	v_lshlrev_b32_e32 v246, 16, v159
	v_and_b32_e32 v247, 0xffff0000, v159
	v_pk_mul_f32 v[62:63], v[62:63], v[246:247]
	v_lshlrev_b32_e32 v252, 16, v180
	v_and_b32_e32 v253, 0xffff0000, v180
	v_pk_add_f32 v[56:57], v[56:57], v[252:253]
	v_lshlrev_b32_e32 v178, 16, v181
	v_and_b32_e32 v179, 0xffff0000, v181
	v_pk_add_f32 v[58:59], v[58:59], v[178:179]
	v_lshlrev_b32_e32 v240, 16, v182
	v_and_b32_e32 v241, 0xffff0000, v182
	v_pk_add_f32 v[60:61], v[60:61], v[240:241]
	v_lshlrev_b32_e32 v244, 16, v183
	v_and_b32_e32 v245, 0xffff0000, v183
	v_pk_add_f32 v[62:63], v[62:63], v[244:245]
	v_cvt_pk_bf16_f32 v156, v56, v57
	v_cvt_pk_bf16_f32 v157, v58, v59
	v_cvt_pk_bf16_f32 v158, v60, v61
	v_cvt_pk_bf16_f32 v159, v62, v63
	s_mov_b32 s58, 0x18000
	v_lshl_add_u64 v[246:247], v[172:173], 0, s[58:59]
	global_store_dwordx4 v[246:247], v[156:159], off offset:256
	s_waitcnt vmcnt(14)
	v_lshlrev_b32_e32 v252, 16, v184
	v_and_b32_e32 v253, 0xffff0000, v184
	v_pk_mul_f32 v[64:65], v[64:65], v[252:253]
	v_lshlrev_b32_e32 v178, 16, v185
	v_and_b32_e32 v179, 0xffff0000, v185
	v_pk_mul_f32 v[66:67], v[66:67], v[178:179]
	v_lshlrev_b32_e32 v240, 16, v186
	v_and_b32_e32 v241, 0xffff0000, v186
	v_pk_mul_f32 v[68:69], v[68:69], v[240:241]
	v_lshlrev_b32_e32 v244, 16, v187
	v_and_b32_e32 v245, 0xffff0000, v187
	v_pk_mul_f32 v[70:71], v[70:71], v[244:245]
	v_lshlrev_b32_e32 v246, 16, v192
	v_and_b32_e32 v247, 0xffff0000, v192
	v_pk_add_f32 v[64:65], v[64:65], v[246:247]
	v_lshlrev_b32_e32 v252, 16, v193
	v_and_b32_e32 v253, 0xffff0000, v193
	v_pk_add_f32 v[66:67], v[66:67], v[252:253]
	v_lshlrev_b32_e32 v178, 16, v194
	v_and_b32_e32 v179, 0xffff0000, v194
	v_pk_add_f32 v[68:69], v[68:69], v[178:179]
	v_lshlrev_b32_e32 v240, 16, v195
	v_and_b32_e32 v241, 0xffff0000, v195
	v_pk_add_f32 v[70:71], v[70:71], v[240:241]
	v_cvt_pk_bf16_f32 v184, v64, v65
	v_cvt_pk_bf16_f32 v185, v66, v67
	v_cvt_pk_bf16_f32 v186, v68, v69
	v_cvt_pk_bf16_f32 v187, v70, v71
	s_mov_b32 s58, 0x40000
	v_lshl_add_u64 v[244:245], v[172:173], 0, s[58:59]
	global_store_dwordx4 v[244:245], v[184:187], off
	s_waitcnt vmcnt(14)
	v_lshlrev_b32_e32 v246, 16, v188
	v_and_b32_e32 v247, 0xffff0000, v188
	v_pk_mul_f32 v[72:73], v[72:73], v[246:247]
	v_lshlrev_b32_e32 v252, 16, v189
	v_and_b32_e32 v253, 0xffff0000, v189
	v_pk_mul_f32 v[74:75], v[74:75], v[252:253]
	v_lshlrev_b32_e32 v178, 16, v190
	v_and_b32_e32 v179, 0xffff0000, v190
	v_pk_mul_f32 v[76:77], v[76:77], v[178:179]
	v_lshlrev_b32_e32 v240, 16, v191
	v_and_b32_e32 v241, 0xffff0000, v191
	v_pk_mul_f32 v[78:79], v[78:79], v[240:241]
	v_lshlrev_b32_e32 v244, 16, v196
	v_and_b32_e32 v245, 0xffff0000, v196
	v_pk_add_f32 v[72:73], v[72:73], v[244:245]
	v_lshlrev_b32_e32 v246, 16, v197
	v_and_b32_e32 v247, 0xffff0000, v197
	v_pk_add_f32 v[74:75], v[74:75], v[246:247]
	v_lshlrev_b32_e32 v252, 16, v198
	v_and_b32_e32 v253, 0xffff0000, v198
	v_pk_add_f32 v[76:77], v[76:77], v[252:253]
	v_lshlrev_b32_e32 v178, 16, v199
	v_and_b32_e32 v179, 0xffff0000, v199
	v_pk_add_f32 v[78:79], v[78:79], v[178:179]
	v_cvt_pk_bf16_f32 v188, v72, v73
	v_cvt_pk_bf16_f32 v189, v74, v75
	v_cvt_pk_bf16_f32 v190, v76, v77
	v_cvt_pk_bf16_f32 v191, v78, v79
	s_mov_b32 s58, 0x40000
	v_lshl_add_u64 v[240:241], v[172:173], 0, s[58:59]
	global_store_dwordx4 v[240:241], v[188:191], off offset:256
	s_waitcnt vmcnt(12)
	v_lshlrev_b32_e32 v244, 16, v236
	v_and_b32_e32 v245, 0xffff0000, v236
	v_pk_mul_f32 v[80:81], v[80:81], v[244:245]
	v_lshlrev_b32_e32 v246, 16, v237
	v_and_b32_e32 v247, 0xffff0000, v237
	v_pk_mul_f32 v[82:83], v[82:83], v[246:247]
	v_lshlrev_b32_e32 v252, 16, v238
	v_and_b32_e32 v253, 0xffff0000, v238
	v_pk_mul_f32 v[84:85], v[84:85], v[252:253]
	v_lshlrev_b32_e32 v178, 16, v239
	v_and_b32_e32 v179, 0xffff0000, v239
	v_pk_mul_f32 v[86:87], v[86:87], v[178:179]
	v_lshlrev_b32_e32 v240, 16, v4
	v_and_b32_e32 v241, 0xffff0000, v4
	v_pk_add_f32 v[80:81], v[80:81], v[240:241]
	v_lshlrev_b32_e32 v244, 16, v5
	v_and_b32_e32 v245, 0xffff0000, v5
	v_pk_add_f32 v[82:83], v[82:83], v[244:245]
	v_lshlrev_b32_e32 v246, 16, v6
	v_and_b32_e32 v247, 0xffff0000, v6
	v_pk_add_f32 v[84:85], v[84:85], v[246:247]
	v_lshlrev_b32_e32 v252, 16, v7
	v_and_b32_e32 v253, 0xffff0000, v7
	v_pk_add_f32 v[86:87], v[86:87], v[252:253]
	v_cvt_pk_bf16_f32 v236, v80, v81
	v_cvt_pk_bf16_f32 v237, v82, v83
	v_cvt_pk_bf16_f32 v238, v84, v85
	v_cvt_pk_bf16_f32 v239, v86, v87
	s_mov_b32 s58, 0x48000
	v_lshl_add_u64 v[178:179], v[172:173], 0, s[58:59]
	global_store_dwordx4 v[178:179], v[236:239], off
	s_waitcnt vmcnt(12)
	v_lshlrev_b32_e32 v240, 16, v0
	v_and_b32_e32 v241, 0xffff0000, v0
	v_pk_mul_f32 v[88:89], v[88:89], v[240:241]
	v_lshlrev_b32_e32 v244, 16, v1
	v_and_b32_e32 v245, 0xffff0000, v1
	v_pk_mul_f32 v[90:91], v[90:91], v[244:245]
	v_lshlrev_b32_e32 v246, 16, v2
	v_and_b32_e32 v247, 0xffff0000, v2
	v_pk_mul_f32 v[92:93], v[92:93], v[246:247]
	v_lshlrev_b32_e32 v252, 16, v3
	v_and_b32_e32 v253, 0xffff0000, v3
	v_pk_mul_f32 v[94:95], v[94:95], v[252:253]
	v_lshlrev_b32_e32 v178, 16, v128
	v_and_b32_e32 v179, 0xffff0000, v128
	v_pk_add_f32 v[88:89], v[88:89], v[178:179]
	v_lshlrev_b32_e32 v240, 16, v129
	v_and_b32_e32 v241, 0xffff0000, v129
	v_pk_add_f32 v[90:91], v[90:91], v[240:241]
	v_lshlrev_b32_e32 v244, 16, v130
	v_and_b32_e32 v245, 0xffff0000, v130
	v_pk_add_f32 v[92:93], v[92:93], v[244:245]
	v_lshlrev_b32_e32 v246, 16, v131
	v_and_b32_e32 v247, 0xffff0000, v131
	v_pk_add_f32 v[94:95], v[94:95], v[246:247]
	v_cvt_pk_bf16_f32 v0, v88, v89
	v_cvt_pk_bf16_f32 v1, v90, v91
	v_cvt_pk_bf16_f32 v2, v92, v93
	v_cvt_pk_bf16_f32 v3, v94, v95
	s_mov_b32 s58, 0x48000
	v_lshl_add_u64 v[252:253], v[172:173], 0, s[58:59]
	global_store_dwordx4 v[252:253], v[0:3], off offset:256
	s_waitcnt vmcnt(10)
	v_lshlrev_b32_e32 v178, 16, v8
	v_and_b32_e32 v179, 0xffff0000, v8
	v_pk_mul_f32 v[96:97], v[96:97], v[178:179]
	v_lshlrev_b32_e32 v240, 16, v9
	v_and_b32_e32 v241, 0xffff0000, v9
	v_pk_mul_f32 v[98:99], v[98:99], v[240:241]
	v_lshlrev_b32_e32 v244, 16, v10
	v_and_b32_e32 v245, 0xffff0000, v10
	v_pk_mul_f32 v[100:101], v[100:101], v[244:245]
	v_lshlrev_b32_e32 v246, 16, v11
	v_and_b32_e32 v247, 0xffff0000, v11
	v_pk_mul_f32 v[102:103], v[102:103], v[246:247]
	v_lshlrev_b32_e32 v252, 16, v132
	v_and_b32_e32 v253, 0xffff0000, v132
	v_pk_add_f32 v[96:97], v[96:97], v[252:253]
	v_lshlrev_b32_e32 v178, 16, v133
	v_and_b32_e32 v179, 0xffff0000, v133
	v_pk_add_f32 v[98:99], v[98:99], v[178:179]
	v_lshlrev_b32_e32 v240, 16, v134
	v_and_b32_e32 v241, 0xffff0000, v134
	v_pk_add_f32 v[100:101], v[100:101], v[240:241]
	v_lshlrev_b32_e32 v244, 16, v135
	v_and_b32_e32 v245, 0xffff0000, v135
	v_pk_add_f32 v[102:103], v[102:103], v[244:245]
	v_cvt_pk_bf16_f32 v8, v96, v97
	v_cvt_pk_bf16_f32 v9, v98, v99
	v_cvt_pk_bf16_f32 v10, v100, v101
	v_cvt_pk_bf16_f32 v11, v102, v103
	s_mov_b32 s58, 0x50000
	v_lshl_add_u64 v[246:247], v[172:173], 0, s[58:59]
	global_store_dwordx4 v[246:247], v[8:11], off
	s_waitcnt vmcnt(10)
	v_lshlrev_b32_e32 v252, 16, v12
	v_and_b32_e32 v253, 0xffff0000, v12
	v_pk_mul_f32 v[104:105], v[104:105], v[252:253]
	v_lshlrev_b32_e32 v178, 16, v13
	v_and_b32_e32 v179, 0xffff0000, v13
	v_pk_mul_f32 v[106:107], v[106:107], v[178:179]
	v_lshlrev_b32_e32 v240, 16, v14
	v_and_b32_e32 v241, 0xffff0000, v14
	v_pk_mul_f32 v[108:109], v[108:109], v[240:241]
	v_lshlrev_b32_e32 v244, 16, v15
	v_and_b32_e32 v245, 0xffff0000, v15
	v_pk_mul_f32 v[110:111], v[110:111], v[244:245]
	v_lshlrev_b32_e32 v246, 16, v16
	v_and_b32_e32 v247, 0xffff0000, v16
	v_pk_add_f32 v[104:105], v[104:105], v[246:247]
	v_lshlrev_b32_e32 v252, 16, v17
	v_and_b32_e32 v253, 0xffff0000, v17
	v_pk_add_f32 v[106:107], v[106:107], v[252:253]
	v_lshlrev_b32_e32 v178, 16, v18
	v_and_b32_e32 v179, 0xffff0000, v18
	v_pk_add_f32 v[108:109], v[108:109], v[178:179]
	v_lshlrev_b32_e32 v240, 16, v19
	v_and_b32_e32 v241, 0xffff0000, v19
	v_pk_add_f32 v[110:111], v[110:111], v[240:241]
	v_cvt_pk_bf16_f32 v12, v104, v105
	v_cvt_pk_bf16_f32 v13, v106, v107
	v_cvt_pk_bf16_f32 v14, v108, v109
	v_cvt_pk_bf16_f32 v15, v110, v111
	s_mov_b32 s58, 0x50000
	v_lshl_add_u64 v[244:245], v[172:173], 0, s[58:59]
	global_store_dwordx4 v[244:245], v[12:15], off offset:256
	s_waitcnt vmcnt(8)
	v_lshlrev_b32_e32 v246, 16, v20
	v_and_b32_e32 v247, 0xffff0000, v20
	v_pk_mul_f32 v[112:113], v[112:113], v[246:247]
	v_lshlrev_b32_e32 v252, 16, v21
	v_and_b32_e32 v253, 0xffff0000, v21
	v_pk_mul_f32 v[114:115], v[114:115], v[252:253]
	v_lshlrev_b32_e32 v178, 16, v22
	v_and_b32_e32 v179, 0xffff0000, v22
	v_pk_mul_f32 v[116:117], v[116:117], v[178:179]
	v_lshlrev_b32_e32 v240, 16, v23
	v_and_b32_e32 v241, 0xffff0000, v23
	v_pk_mul_f32 v[118:119], v[118:119], v[240:241]
	v_lshlrev_b32_e32 v244, 16, v24
	v_and_b32_e32 v245, 0xffff0000, v24
	v_pk_add_f32 v[112:113], v[112:113], v[244:245]
	v_lshlrev_b32_e32 v246, 16, v25
	v_and_b32_e32 v247, 0xffff0000, v25
	v_pk_add_f32 v[114:115], v[114:115], v[246:247]
	v_lshlrev_b32_e32 v252, 16, v26
	v_and_b32_e32 v253, 0xffff0000, v26
	v_pk_add_f32 v[116:117], v[116:117], v[252:253]
	v_lshlrev_b32_e32 v178, 16, v27
	v_and_b32_e32 v179, 0xffff0000, v27
	v_pk_add_f32 v[118:119], v[118:119], v[178:179]
	v_cvt_pk_bf16_f32 v20, v112, v113
	v_cvt_pk_bf16_f32 v21, v114, v115
	v_cvt_pk_bf16_f32 v22, v116, v117
	v_cvt_pk_bf16_f32 v23, v118, v119
	s_mov_b32 s58, 0x58000
	v_lshl_add_u64 v[240:241], v[172:173], 0, s[58:59]
	global_store_dwordx4 v[240:241], v[20:23], off
	s_waitcnt vmcnt(8)
	v_lshlrev_b32_e32 v244, 16, v136
	v_and_b32_e32 v245, 0xffff0000, v136
	v_pk_mul_f32 v[120:121], v[120:121], v[244:245]
	v_lshlrev_b32_e32 v246, 16, v137
	v_and_b32_e32 v247, 0xffff0000, v137
	v_pk_mul_f32 v[122:123], v[122:123], v[246:247]
	v_lshlrev_b32_e32 v252, 16, v138
	v_and_b32_e32 v253, 0xffff0000, v138
	v_pk_mul_f32 v[124:125], v[124:125], v[252:253]
	v_lshlrev_b32_e32 v178, 16, v139
	v_and_b32_e32 v179, 0xffff0000, v139
	v_pk_mul_f32 v[126:127], v[126:127], v[178:179]
	v_lshlrev_b32_e32 v240, 16, v28
	v_and_b32_e32 v241, 0xffff0000, v28
	v_pk_add_f32 v[120:121], v[120:121], v[240:241]
	v_lshlrev_b32_e32 v244, 16, v29
	v_and_b32_e32 v245, 0xffff0000, v29
	v_pk_add_f32 v[122:123], v[122:123], v[244:245]
	v_lshlrev_b32_e32 v246, 16, v30
	v_and_b32_e32 v247, 0xffff0000, v30
	v_pk_add_f32 v[124:125], v[124:125], v[246:247]
	v_lshlrev_b32_e32 v252, 16, v31
	v_and_b32_e32 v253, 0xffff0000, v31
	v_pk_add_f32 v[126:127], v[126:127], v[252:253]
	v_cvt_pk_bf16_f32 v136, v120, v121
	v_cvt_pk_bf16_f32 v137, v122, v123
	v_cvt_pk_bf16_f32 v138, v124, v125
	v_cvt_pk_bf16_f32 v139, v126, v127
	s_mov_b32 s58, 0x58000
	v_lshl_add_u64 v[178:179], v[172:173], 0, s[58:59]
	global_store_dwordx4 v[178:179], v[136:139], off offset:256
	s_branch .Lmepi_done
.Lmepi_z3:
	global_load_dwordx4 v[128:131], v[170:171], off nt
	global_load_dwordx4 v[132:135], v[170:171], off offset:256 nt
	s_mov_b32 s58, 0x20000
	v_lshl_add_u64 v[244:245], v[170:171], 0, s[58:59]
	global_load_dwordx4 v[136:139], v[244:245], off nt
	global_load_dwordx4 v[140:143], v[244:245], off offset:256 nt
	s_mov_b32 s58, 0x40000
	v_lshl_add_u64 v[246:247], v[170:171], 0, s[58:59]
	global_load_dwordx4 v[144:147], v[246:247], off nt
	global_load_dwordx4 v[148:151], v[246:247], off offset:256 nt
	s_mov_b32 s58, 0x60000
	v_lshl_add_u64 v[252:253], v[170:171], 0, s[58:59]
	global_load_dwordx4 v[152:155], v[252:253], off nt
	global_load_dwordx4 v[156:159], v[252:253], off offset:256 nt
	s_mov_b32 s58, 0x18000
	v_lshl_add_u64 v[178:179], v[172:173], 0, s[58:59]
	global_load_dwordx4 v[180:183], v[178:179], off offset:256
	s_mov_b32 s58, 0x100000
	v_lshl_add_u64 v[240:241], v[170:171], 0, s[58:59]
	global_load_dwordx4 v[184:187], v[240:241], off nt
	global_load_dwordx4 v[188:191], v[240:241], off offset:256 nt
	s_mov_b32 s58, 0x40000
	v_lshl_add_u64 v[244:245], v[172:173], 0, s[58:59]
	global_load_dwordx4 v[192:195], v[244:245], off
	global_load_dwordx4 v[196:199], v[244:245], off offset:256
	s_waitcnt vmcnt(12)
	v_lshlrev_b32_e32 v246, 16, v128
	v_and_b32_e32 v247, 0xffff0000, v128
	v_pk_mul_f32 v[0:1], v[0:1], v[246:247]
	v_lshlrev_b32_e32 v252, 16, v129
	v_and_b32_e32 v253, 0xffff0000, v129
	v_pk_mul_f32 v[2:3], v[2:3], v[252:253]
	v_lshlrev_b32_e32 v178, 16, v130
	v_and_b32_e32 v179, 0xffff0000, v130
	v_pk_mul_f32 v[4:5], v[4:5], v[178:179]
	v_lshlrev_b32_e32 v240, 16, v131
	v_and_b32_e32 v241, 0xffff0000, v131
	v_pk_mul_f32 v[6:7], v[6:7], v[240:241]
	v_lshlrev_b32_e32 v244, 16, v200
	v_and_b32_e32 v245, 0xffff0000, v200
	v_pk_add_f32 v[0:1], v[0:1], v[244:245]
	v_lshlrev_b32_e32 v246, 16, v201
	v_and_b32_e32 v247, 0xffff0000, v201
	v_pk_add_f32 v[2:3], v[2:3], v[246:247]
	v_lshlrev_b32_e32 v252, 16, v202
	v_and_b32_e32 v253, 0xffff0000, v202
	v_pk_add_f32 v[4:5], v[4:5], v[252:253]
	v_lshlrev_b32_e32 v178, 16, v203
	v_and_b32_e32 v179, 0xffff0000, v203
	v_pk_add_f32 v[6:7], v[6:7], v[178:179]
	v_cvt_pk_bf16_f32 v128, v0, v1
	v_cvt_pk_bf16_f32 v129, v2, v3
	v_cvt_pk_bf16_f32 v130, v4, v5
	v_cvt_pk_bf16_f32 v131, v6, v7
	global_store_dwordx4 v[172:173], v[128:131], off sc1
	s_waitcnt vmcnt(12)
	v_lshlrev_b32_e32 v240, 16, v132
	v_and_b32_e32 v241, 0xffff0000, v132
	v_pk_mul_f32 v[8:9], v[8:9], v[240:241]
	v_lshlrev_b32_e32 v244, 16, v133
	v_and_b32_e32 v245, 0xffff0000, v133
	v_pk_mul_f32 v[10:11], v[10:11], v[244:245]
	v_lshlrev_b32_e32 v246, 16, v134
	v_and_b32_e32 v247, 0xffff0000, v134
	v_pk_mul_f32 v[12:13], v[12:13], v[246:247]
	v_lshlrev_b32_e32 v252, 16, v135
	v_and_b32_e32 v253, 0xffff0000, v135
	v_pk_mul_f32 v[14:15], v[14:15], v[252:253]
	v_lshlrev_b32_e32 v178, 16, v204
	v_and_b32_e32 v179, 0xffff0000, v204
	v_pk_add_f32 v[8:9], v[8:9], v[178:179]
	v_lshlrev_b32_e32 v240, 16, v205
	v_and_b32_e32 v241, 0xffff0000, v205
	v_pk_add_f32 v[10:11], v[10:11], v[240:241]
	v_lshlrev_b32_e32 v244, 16, v206
	v_and_b32_e32 v245, 0xffff0000, v206
	v_pk_add_f32 v[12:13], v[12:13], v[244:245]
	v_lshlrev_b32_e32 v246, 16, v207
	v_and_b32_e32 v247, 0xffff0000, v207
	v_pk_add_f32 v[14:15], v[14:15], v[246:247]
	v_cvt_pk_bf16_f32 v132, v8, v9
	v_cvt_pk_bf16_f32 v133, v10, v11
	v_cvt_pk_bf16_f32 v134, v12, v13
	v_cvt_pk_bf16_f32 v135, v14, v15
	global_store_dwordx4 v[172:173], v[132:135], off offset:256 sc1
	s_mov_b32 s58, 0x120000
	v_lshl_add_u64 v[252:253], v[170:171], 0, s[58:59]
	global_load_dwordx4 v[236:239], v[252:253], off nt
	global_load_dwordx4 v[0:3], v[252:253], off offset:256 nt
	s_mov_b32 s58, 0x48000
	v_lshl_add_u64 v[178:179], v[172:173], 0, s[58:59]
	global_load_dwordx4 v[4:7], v[178:179], off
	global_load_dwordx4 v[128:131], v[178:179], off offset:256
	s_waitcnt vmcnt(16)
	v_lshlrev_b32_e32 v240, 16, v136
	v_and_b32_e32 v241, 0xffff0000, v136
	v_pk_mul_f32 v[16:17], v[16:17], v[240:241]
	v_lshlrev_b32_e32 v244, 16, v137
	v_and_b32_e32 v245, 0xffff0000, v137
	v_pk_mul_f32 v[18:19], v[18:19], v[244:245]
	v_lshlrev_b32_e32 v246, 16, v138
	v_and_b32_e32 v247, 0xffff0000, v138
	v_pk_mul_f32 v[20:21], v[20:21], v[246:247]
	v_lshlrev_b32_e32 v252, 16, v139
	v_and_b32_e32 v253, 0xffff0000, v139
	v_pk_mul_f32 v[22:23], v[22:23], v[252:253]
	v_lshlrev_b32_e32 v178, 16, v208
	v_and_b32_e32 v179, 0xffff0000, v208
	v_pk_add_f32 v[16:17], v[16:17], v[178:179]
	v_lshlrev_b32_e32 v240, 16, v209
	v_and_b32_e32 v241, 0xffff0000, v209
	v_pk_add_f32 v[18:19], v[18:19], v[240:241]
	v_lshlrev_b32_e32 v244, 16, v210
	v_and_b32_e32 v245, 0xffff0000, v210
	v_pk_add_f32 v[20:21], v[20:21], v[244:245]
	v_lshlrev_b32_e32 v246, 16, v211
	v_and_b32_e32 v247, 0xffff0000, v211
	v_pk_add_f32 v[22:23], v[22:23], v[246:247]
	v_cvt_pk_bf16_f32 v136, v16, v17
	v_cvt_pk_bf16_f32 v137, v18, v19
	v_cvt_pk_bf16_f32 v138, v20, v21
	v_cvt_pk_bf16_f32 v139, v22, v23
	s_mov_b32 s58, 0x8000
	v_lshl_add_u64 v[252:253], v[172:173], 0, s[58:59]
	global_store_dwordx4 v[252:253], v[136:139], off sc1
	s_waitcnt vmcnt(16)
	v_lshlrev_b32_e32 v178, 16, v140
	v_and_b32_e32 v179, 0xffff0000, v140
	v_pk_mul_f32 v[24:25], v[24:25], v[178:179]
	v_lshlrev_b32_e32 v240, 16, v141
	v_and_b32_e32 v241, 0xffff0000, v141
	v_pk_mul_f32 v[26:27], v[26:27], v[240:241]
	v_lshlrev_b32_e32 v244, 16, v142
	v_and_b32_e32 v245, 0xffff0000, v142
	v_pk_mul_f32 v[28:29], v[28:29], v[244:245]
	v_lshlrev_b32_e32 v246, 16, v143
	v_and_b32_e32 v247, 0xffff0000, v143
	v_pk_mul_f32 v[30:31], v[30:31], v[246:247]
	v_lshlrev_b32_e32 v252, 16, v212
	v_and_b32_e32 v253, 0xffff0000, v212
	v_pk_add_f32 v[24:25], v[24:25], v[252:253]
	v_lshlrev_b32_e32 v178, 16, v213
	v_and_b32_e32 v179, 0xffff0000, v213
	v_pk_add_f32 v[26:27], v[26:27], v[178:179]
	v_lshlrev_b32_e32 v240, 16, v214
	v_and_b32_e32 v241, 0xffff0000, v214
	v_pk_add_f32 v[28:29], v[28:29], v[240:241]
	v_lshlrev_b32_e32 v244, 16, v215
	v_and_b32_e32 v245, 0xffff0000, v215
	v_pk_add_f32 v[30:31], v[30:31], v[244:245]
	v_cvt_pk_bf16_f32 v140, v24, v25
	v_cvt_pk_bf16_f32 v141, v26, v27
	v_cvt_pk_bf16_f32 v142, v28, v29
	v_cvt_pk_bf16_f32 v143, v30, v31
	s_mov_b32 s58, 0x8000
	v_lshl_add_u64 v[246:247], v[172:173], 0, s[58:59]
	global_store_dwordx4 v[246:247], v[140:143], off offset:256 sc1
	s_mov_b32 s58, 0x140000
	v_lshl_add_u64 v[252:253], v[170:171], 0, s[58:59]
	global_load_dwordx4 v[8:11], v[252:253], off nt
	global_load_dwordx4 v[12:15], v[252:253], off offset:256 nt
	s_mov_b32 s58, 0x50000
	v_lshl_add_u64 v[178:179], v[172:173], 0, s[58:59]
	global_load_dwordx4 v[132:135], v[178:179], off
	global_load_dwordx4 v[16:19], v[178:179], off offset:256
	s_mov_b32 s58, 0x160000
	v_lshl_add_u64 v[240:241], v[170:171], 0, s[58:59]
	global_load_dwordx4 v[20:23], v[240:241], off nt
	global_load_dwordx4 v[136:139], v[240:241], off offset:256 nt
	s_mov_b32 s58, 0x58000
	v_lshl_add_u64 v[244:245], v[172:173], 0, s[58:59]
	global_load_dwordx4 v[24:27], v[244:245], off
	global_load_dwordx4 v[28:31], v[244:245], off offset:256
	s_waitcnt vmcnt(24)
	v_lshlrev_b32_e32 v246, 16, v144
	v_and_b32_e32 v247, 0xffff0000, v144
	v_pk_mul_f32 v[32:33], v[32:33], v[246:247]
	v_lshlrev_b32_e32 v252, 16, v145
	v_and_b32_e32 v253, 0xffff0000, v145
	v_pk_mul_f32 v[34:35], v[34:35], v[252:253]
	v_lshlrev_b32_e32 v178, 16, v146
	v_and_b32_e32 v179, 0xffff0000, v146
	v_pk_mul_f32 v[36:37], v[36:37], v[178:179]
	v_lshlrev_b32_e32 v240, 16, v147
	v_and_b32_e32 v241, 0xffff0000, v147
	v_pk_mul_f32 v[38:39], v[38:39], v[240:241]
	v_lshlrev_b32_e32 v244, 16, v216
	v_and_b32_e32 v245, 0xffff0000, v216
	v_pk_add_f32 v[32:33], v[32:33], v[244:245]
	v_lshlrev_b32_e32 v246, 16, v217
	v_and_b32_e32 v247, 0xffff0000, v217
	v_pk_add_f32 v[34:35], v[34:35], v[246:247]
	v_lshlrev_b32_e32 v252, 16, v218
	v_and_b32_e32 v253, 0xffff0000, v218
	v_pk_add_f32 v[36:37], v[36:37], v[252:253]
	v_lshlrev_b32_e32 v178, 16, v219
	v_and_b32_e32 v179, 0xffff0000, v219
	v_pk_add_f32 v[38:39], v[38:39], v[178:179]
	v_cvt_pk_bf16_f32 v144, v32, v33
	v_cvt_pk_bf16_f32 v145, v34, v35
	v_cvt_pk_bf16_f32 v146, v36, v37
	v_cvt_pk_bf16_f32 v147, v38, v39
	s_mov_b32 s58, 0x10000
	v_lshl_add_u64 v[240:241], v[172:173], 0, s[58:59]
	global_store_dwordx4 v[240:241], v[144:147], off sc1
	s_waitcnt vmcnt(24)
	v_lshlrev_b32_e32 v244, 16, v148
	v_and_b32_e32 v245, 0xffff0000, v148
	v_pk_mul_f32 v[40:41], v[40:41], v[244:245]
	v_lshlrev_b32_e32 v246, 16, v149
	v_and_b32_e32 v247, 0xffff0000, v149
	v_pk_mul_f32 v[42:43], v[42:43], v[246:247]
	v_lshlrev_b32_e32 v252, 16, v150
	v_and_b32_e32 v253, 0xffff0000, v150
	v_pk_mul_f32 v[44:45], v[44:45], v[252:253]
	v_lshlrev_b32_e32 v178, 16, v151
	v_and_b32_e32 v179, 0xffff0000, v151
	v_pk_mul_f32 v[46:47], v[46:47], v[178:179]
	v_lshlrev_b32_e32 v240, 16, v220
	v_and_b32_e32 v241, 0xffff0000, v220
	v_pk_add_f32 v[40:41], v[40:41], v[240:241]
	v_lshlrev_b32_e32 v244, 16, v221
	v_and_b32_e32 v245, 0xffff0000, v221
	v_pk_add_f32 v[42:43], v[42:43], v[244:245]
	v_lshlrev_b32_e32 v246, 16, v222
	v_and_b32_e32 v247, 0xffff0000, v222
	v_pk_add_f32 v[44:45], v[44:45], v[246:247]
	v_lshlrev_b32_e32 v252, 16, v223
	v_and_b32_e32 v253, 0xffff0000, v223
	v_pk_add_f32 v[46:47], v[46:47], v[252:253]
	v_cvt_pk_bf16_f32 v148, v40, v41
	v_cvt_pk_bf16_f32 v149, v42, v43
	v_cvt_pk_bf16_f32 v150, v44, v45
	v_cvt_pk_bf16_f32 v151, v46, v47
	s_mov_b32 s58, 0x10000
	v_lshl_add_u64 v[178:179], v[172:173], 0, s[58:59]
	global_store_dwordx4 v[178:179], v[148:151], off offset:256 sc1
	s_waitcnt vmcnt(24)
	v_lshlrev_b32_e32 v240, 16, v152
	v_and_b32_e32 v241, 0xffff0000, v152
	v_pk_mul_f32 v[48:49], v[48:49], v[240:241]
	v_lshlrev_b32_e32 v244, 16, v153
	v_and_b32_e32 v245, 0xffff0000, v153
	v_pk_mul_f32 v[50:51], v[50:51], v[244:245]
	v_lshlrev_b32_e32 v246, 16, v154
	v_and_b32_e32 v247, 0xffff0000, v154
	v_pk_mul_f32 v[52:53], v[52:53], v[246:247]
	v_lshlrev_b32_e32 v252, 16, v155
	v_and_b32_e32 v253, 0xffff0000, v155
	v_pk_mul_f32 v[54:55], v[54:55], v[252:253]
	v_lshlrev_b32_e32 v178, 16, v224
	v_and_b32_e32 v179, 0xffff0000, v224
	v_pk_add_f32 v[48:49], v[48:49], v[178:179]
	v_lshlrev_b32_e32 v240, 16, v225
	v_and_b32_e32 v241, 0xffff0000, v225
	v_pk_add_f32 v[50:51], v[50:51], v[240:241]
	v_lshlrev_b32_e32 v244, 16, v226
	v_and_b32_e32 v245, 0xffff0000, v226
	v_pk_add_f32 v[52:53], v[52:53], v[244:245]
	v_lshlrev_b32_e32 v246, 16, v227
	v_and_b32_e32 v247, 0xffff0000, v227
	v_pk_add_f32 v[54:55], v[54:55], v[246:247]
	v_cvt_pk_bf16_f32 v152, v48, v49
	v_cvt_pk_bf16_f32 v153, v50, v51
	v_cvt_pk_bf16_f32 v154, v52, v53
	v_cvt_pk_bf16_f32 v155, v54, v55
	s_mov_b32 s58, 0x18000
	v_lshl_add_u64 v[252:253], v[172:173], 0, s[58:59]
	global_store_dwordx4 v[252:253], v[152:155], off sc1
	s_waitcnt vmcnt(23)
	v_lshlrev_b32_e32 v178, 16, v156
	v_and_b32_e32 v179, 0xffff0000, v156
	v_pk_mul_f32 v[56:57], v[56:57], v[178:179]
	v_lshlrev_b32_e32 v240, 16, v157
	v_and_b32_e32 v241, 0xffff0000, v157
	v_pk_mul_f32 v[58:59], v[58:59], v[240:241]
	v_lshlrev_b32_e32 v244, 16, v158
	v_and_b32_e32 v245, 0xffff0000, v158
	v_pk_mul_f32 v[60:61], v[60:61], v[244:245]
	v_lshlrev_b32_e32 v246, 16, v159
	v_and_b32_e32 v247, 0xffff0000, v159
	v_pk_mul_f32 v[62:63], v[62:63], v[246:247]
	v_lshlrev_b32_e32 v252, 16, v180
	v_and_b32_e32 v253, 0xffff0000, v180
	v_pk_add_f32 v[56:57], v[56:57], v[252:253]
	v_lshlrev_b32_e32 v178, 16, v181
	v_and_b32_e32 v179, 0xffff0000, v181
	v_pk_add_f32 v[58:59], v[58:59], v[178:179]
	v_lshlrev_b32_e32 v240, 16, v182
	v_and_b32_e32 v241, 0xffff0000, v182
	v_pk_add_f32 v[60:61], v[60:61], v[240:241]
	v_lshlrev_b32_e32 v244, 16, v183
	v_and_b32_e32 v245, 0xffff0000, v183
	v_pk_add_f32 v[62:63], v[62:63], v[244:245]
	v_cvt_pk_bf16_f32 v156, v56, v57
	v_cvt_pk_bf16_f32 v157, v58, v59
	v_cvt_pk_bf16_f32 v158, v60, v61
	v_cvt_pk_bf16_f32 v159, v62, v63
	s_mov_b32 s58, 0x18000
	v_lshl_add_u64 v[246:247], v[172:173], 0, s[58:59]
	global_store_dwordx4 v[246:247], v[156:159], off offset:256 sc1
	s_waitcnt vmcnt(21)
	v_lshlrev_b32_e32 v252, 16, v184
	v_and_b32_e32 v253, 0xffff0000, v184
	v_pk_mul_f32 v[64:65], v[64:65], v[252:253]
	v_lshlrev_b32_e32 v178, 16, v185
	v_and_b32_e32 v179, 0xffff0000, v185
	v_pk_mul_f32 v[66:67], v[66:67], v[178:179]
	v_lshlrev_b32_e32 v240, 16, v186
	v_and_b32_e32 v241, 0xffff0000, v186
	v_pk_mul_f32 v[68:69], v[68:69], v[240:241]
	v_lshlrev_b32_e32 v244, 16, v187
	v_and_b32_e32 v245, 0xffff0000, v187
	v_pk_mul_f32 v[70:71], v[70:71], v[244:245]
	v_lshlrev_b32_e32 v246, 16, v192
	v_and_b32_e32 v247, 0xffff0000, v192
	v_pk_add_f32 v[64:65], v[64:65], v[246:247]
	v_lshlrev_b32_e32 v252, 16, v193
	v_and_b32_e32 v253, 0xffff0000, v193
	v_pk_add_f32 v[66:67], v[66:67], v[252:253]
	v_lshlrev_b32_e32 v178, 16, v194
	v_and_b32_e32 v179, 0xffff0000, v194
	v_pk_add_f32 v[68:69], v[68:69], v[178:179]
	v_lshlrev_b32_e32 v240, 16, v195
	v_and_b32_e32 v241, 0xffff0000, v195
	v_pk_add_f32 v[70:71], v[70:71], v[240:241]
	v_cvt_pk_bf16_f32 v184, v64, v65
	v_cvt_pk_bf16_f32 v185, v66, v67
	v_cvt_pk_bf16_f32 v186, v68, v69
	v_cvt_pk_bf16_f32 v187, v70, v71
	s_mov_b32 s58, 0x40000
	v_lshl_add_u64 v[244:245], v[172:173], 0, s[58:59]
	global_store_dwordx4 v[244:245], v[184:187], off sc1
	s_waitcnt vmcnt(21)
	v_lshlrev_b32_e32 v246, 16, v188
	v_and_b32_e32 v247, 0xffff0000, v188
	v_pk_mul_f32 v[72:73], v[72:73], v[246:247]
	v_lshlrev_b32_e32 v252, 16, v189
	v_and_b32_e32 v253, 0xffff0000, v189
	v_pk_mul_f32 v[74:75], v[74:75], v[252:253]
	v_lshlrev_b32_e32 v178, 16, v190
	v_and_b32_e32 v179, 0xffff0000, v190
	v_pk_mul_f32 v[76:77], v[76:77], v[178:179]
	v_lshlrev_b32_e32 v240, 16, v191
	v_and_b32_e32 v241, 0xffff0000, v191
	v_pk_mul_f32 v[78:79], v[78:79], v[240:241]
	v_lshlrev_b32_e32 v244, 16, v196
	v_and_b32_e32 v245, 0xffff0000, v196
	v_pk_add_f32 v[72:73], v[72:73], v[244:245]
	v_lshlrev_b32_e32 v246, 16, v197
	v_and_b32_e32 v247, 0xffff0000, v197
	v_pk_add_f32 v[74:75], v[74:75], v[246:247]
	v_lshlrev_b32_e32 v252, 16, v198
	v_and_b32_e32 v253, 0xffff0000, v198
	v_pk_add_f32 v[76:77], v[76:77], v[252:253]
	v_lshlrev_b32_e32 v178, 16, v199
	v_and_b32_e32 v179, 0xffff0000, v199
	v_pk_add_f32 v[78:79], v[78:79], v[178:179]
	v_cvt_pk_bf16_f32 v188, v72, v73
	v_cvt_pk_bf16_f32 v189, v74, v75
	v_cvt_pk_bf16_f32 v190, v76, v77
	v_cvt_pk_bf16_f32 v191, v78, v79
	s_mov_b32 s58, 0x40000
	v_lshl_add_u64 v[240:241], v[172:173], 0, s[58:59]
	global_store_dwordx4 v[240:241], v[188:191], off offset:256 sc1
	s_waitcnt vmcnt(17)
	v_lshlrev_b32_e32 v244, 16, v236
	v_and_b32_e32 v245, 0xffff0000, v236
	v_pk_mul_f32 v[80:81], v[80:81], v[244:245]
	v_lshlrev_b32_e32 v246, 16, v237
	v_and_b32_e32 v247, 0xffff0000, v237
	v_pk_mul_f32 v[82:83], v[82:83], v[246:247]
	v_lshlrev_b32_e32 v252, 16, v238
	v_and_b32_e32 v253, 0xffff0000, v238
	v_pk_mul_f32 v[84:85], v[84:85], v[252:253]
	v_lshlrev_b32_e32 v178, 16, v239
	v_and_b32_e32 v179, 0xffff0000, v239
	v_pk_mul_f32 v[86:87], v[86:87], v[178:179]
	v_lshlrev_b32_e32 v240, 16, v4
	v_and_b32_e32 v241, 0xffff0000, v4
	v_pk_add_f32 v[80:81], v[80:81], v[240:241]
	v_lshlrev_b32_e32 v244, 16, v5
	v_and_b32_e32 v245, 0xffff0000, v5
	v_pk_add_f32 v[82:83], v[82:83], v[244:245]
	v_lshlrev_b32_e32 v246, 16, v6
	v_and_b32_e32 v247, 0xffff0000, v6
	v_pk_add_f32 v[84:85], v[84:85], v[246:247]
	v_lshlrev_b32_e32 v252, 16, v7
	v_and_b32_e32 v253, 0xffff0000, v7
	v_pk_add_f32 v[86:87], v[86:87], v[252:253]
	v_cvt_pk_bf16_f32 v236, v80, v81
	v_cvt_pk_bf16_f32 v237, v82, v83
	v_cvt_pk_bf16_f32 v238, v84, v85
	v_cvt_pk_bf16_f32 v239, v86, v87
	s_mov_b32 s58, 0x48000
	v_lshl_add_u64 v[178:179], v[172:173], 0, s[58:59]
	global_store_dwordx4 v[178:179], v[236:239], off sc1
	s_waitcnt vmcnt(17)
	v_lshlrev_b32_e32 v240, 16, v0
	v_and_b32_e32 v241, 0xffff0000, v0
	v_pk_mul_f32 v[88:89], v[88:89], v[240:241]
	v_lshlrev_b32_e32 v244, 16, v1
	v_and_b32_e32 v245, 0xffff0000, v1
	v_pk_mul_f32 v[90:91], v[90:91], v[244:245]
	v_lshlrev_b32_e32 v246, 16, v2
	v_and_b32_e32 v247, 0xffff0000, v2
	v_pk_mul_f32 v[92:93], v[92:93], v[246:247]
	v_lshlrev_b32_e32 v252, 16, v3
	v_and_b32_e32 v253, 0xffff0000, v3
	v_pk_mul_f32 v[94:95], v[94:95], v[252:253]
	v_lshlrev_b32_e32 v178, 16, v128
	v_and_b32_e32 v179, 0xffff0000, v128
	v_pk_add_f32 v[88:89], v[88:89], v[178:179]
	v_lshlrev_b32_e32 v240, 16, v129
	v_and_b32_e32 v241, 0xffff0000, v129
	v_pk_add_f32 v[90:91], v[90:91], v[240:241]
	v_lshlrev_b32_e32 v244, 16, v130
	v_and_b32_e32 v245, 0xffff0000, v130
	v_pk_add_f32 v[92:93], v[92:93], v[244:245]
	v_lshlrev_b32_e32 v246, 16, v131
	v_and_b32_e32 v247, 0xffff0000, v131
	v_pk_add_f32 v[94:95], v[94:95], v[246:247]
	v_cvt_pk_bf16_f32 v0, v88, v89
	v_cvt_pk_bf16_f32 v1, v90, v91
	v_cvt_pk_bf16_f32 v2, v92, v93
	v_cvt_pk_bf16_f32 v3, v94, v95
	s_mov_b32 s58, 0x48000
	v_lshl_add_u64 v[252:253], v[172:173], 0, s[58:59]
	global_store_dwordx4 v[252:253], v[0:3], off offset:256 sc1
	s_waitcnt vmcnt(13)
	v_lshlrev_b32_e32 v178, 16, v8
	v_and_b32_e32 v179, 0xffff0000, v8
	v_pk_mul_f32 v[96:97], v[96:97], v[178:179]
	v_lshlrev_b32_e32 v240, 16, v9
	v_and_b32_e32 v241, 0xffff0000, v9
	v_pk_mul_f32 v[98:99], v[98:99], v[240:241]
	v_lshlrev_b32_e32 v244, 16, v10
	v_and_b32_e32 v245, 0xffff0000, v10
	v_pk_mul_f32 v[100:101], v[100:101], v[244:245]
	v_lshlrev_b32_e32 v246, 16, v11
	v_and_b32_e32 v247, 0xffff0000, v11
	v_pk_mul_f32 v[102:103], v[102:103], v[246:247]
	v_lshlrev_b32_e32 v252, 16, v132
	v_and_b32_e32 v253, 0xffff0000, v132
	v_pk_add_f32 v[96:97], v[96:97], v[252:253]
	v_lshlrev_b32_e32 v178, 16, v133
	v_and_b32_e32 v179, 0xffff0000, v133
	v_pk_add_f32 v[98:99], v[98:99], v[178:179]
	v_lshlrev_b32_e32 v240, 16, v134
	v_and_b32_e32 v241, 0xffff0000, v134
	v_pk_add_f32 v[100:101], v[100:101], v[240:241]
	v_lshlrev_b32_e32 v244, 16, v135
	v_and_b32_e32 v245, 0xffff0000, v135
	v_pk_add_f32 v[102:103], v[102:103], v[244:245]
	v_cvt_pk_bf16_f32 v8, v96, v97
	v_cvt_pk_bf16_f32 v9, v98, v99
	v_cvt_pk_bf16_f32 v10, v100, v101
	v_cvt_pk_bf16_f32 v11, v102, v103
	s_mov_b32 s58, 0x50000
	v_lshl_add_u64 v[246:247], v[172:173], 0, s[58:59]
	global_store_dwordx4 v[246:247], v[8:11], off sc1
	s_waitcnt vmcnt(13)
	v_lshlrev_b32_e32 v252, 16, v12
	v_and_b32_e32 v253, 0xffff0000, v12
	v_pk_mul_f32 v[104:105], v[104:105], v[252:253]
	v_lshlrev_b32_e32 v178, 16, v13
	v_and_b32_e32 v179, 0xffff0000, v13
	v_pk_mul_f32 v[106:107], v[106:107], v[178:179]
	v_lshlrev_b32_e32 v240, 16, v14
	v_and_b32_e32 v241, 0xffff0000, v14
	v_pk_mul_f32 v[108:109], v[108:109], v[240:241]
	v_lshlrev_b32_e32 v244, 16, v15
	v_and_b32_e32 v245, 0xffff0000, v15
	v_pk_mul_f32 v[110:111], v[110:111], v[244:245]
	v_lshlrev_b32_e32 v246, 16, v16
	v_and_b32_e32 v247, 0xffff0000, v16
	v_pk_add_f32 v[104:105], v[104:105], v[246:247]
	v_lshlrev_b32_e32 v252, 16, v17
	v_and_b32_e32 v253, 0xffff0000, v17
	v_pk_add_f32 v[106:107], v[106:107], v[252:253]
	v_lshlrev_b32_e32 v178, 16, v18
	v_and_b32_e32 v179, 0xffff0000, v18
	v_pk_add_f32 v[108:109], v[108:109], v[178:179]
	v_lshlrev_b32_e32 v240, 16, v19
	v_and_b32_e32 v241, 0xffff0000, v19
	v_pk_add_f32 v[110:111], v[110:111], v[240:241]
	v_cvt_pk_bf16_f32 v12, v104, v105
	v_cvt_pk_bf16_f32 v13, v106, v107
	v_cvt_pk_bf16_f32 v14, v108, v109
	v_cvt_pk_bf16_f32 v15, v110, v111
	s_mov_b32 s58, 0x50000
	v_lshl_add_u64 v[244:245], v[172:173], 0, s[58:59]
	global_store_dwordx4 v[244:245], v[12:15], off offset:256 sc1
	s_waitcnt vmcnt(11)
	v_lshlrev_b32_e32 v246, 16, v20
	v_and_b32_e32 v247, 0xffff0000, v20
	v_pk_mul_f32 v[112:113], v[112:113], v[246:247]
	v_lshlrev_b32_e32 v252, 16, v21
	v_and_b32_e32 v253, 0xffff0000, v21
	v_pk_mul_f32 v[114:115], v[114:115], v[252:253]
	v_lshlrev_b32_e32 v178, 16, v22
	v_and_b32_e32 v179, 0xffff0000, v22
	v_pk_mul_f32 v[116:117], v[116:117], v[178:179]
	v_lshlrev_b32_e32 v240, 16, v23
	v_and_b32_e32 v241, 0xffff0000, v23
	v_pk_mul_f32 v[118:119], v[118:119], v[240:241]
	v_lshlrev_b32_e32 v244, 16, v24
	v_and_b32_e32 v245, 0xffff0000, v24
	v_pk_add_f32 v[112:113], v[112:113], v[244:245]
	v_lshlrev_b32_e32 v246, 16, v25
	v_and_b32_e32 v247, 0xffff0000, v25
	v_pk_add_f32 v[114:115], v[114:115], v[246:247]
	v_lshlrev_b32_e32 v252, 16, v26
	v_and_b32_e32 v253, 0xffff0000, v26
	v_pk_add_f32 v[116:117], v[116:117], v[252:253]
	v_lshlrev_b32_e32 v178, 16, v27
	v_and_b32_e32 v179, 0xffff0000, v27
	v_pk_add_f32 v[118:119], v[118:119], v[178:179]
	v_cvt_pk_bf16_f32 v20, v112, v113
	v_cvt_pk_bf16_f32 v21, v114, v115
	v_cvt_pk_bf16_f32 v22, v116, v117
	v_cvt_pk_bf16_f32 v23, v118, v119
	s_mov_b32 s58, 0x58000
	v_lshl_add_u64 v[240:241], v[172:173], 0, s[58:59]
	global_store_dwordx4 v[240:241], v[20:23], off sc1
	s_waitcnt vmcnt(11)
	v_lshlrev_b32_e32 v244, 16, v136
	v_and_b32_e32 v245, 0xffff0000, v136
	v_pk_mul_f32 v[120:121], v[120:121], v[244:245]
	v_lshlrev_b32_e32 v246, 16, v137
	v_and_b32_e32 v247, 0xffff0000, v137
	v_pk_mul_f32 v[122:123], v[122:123], v[246:247]
	v_lshlrev_b32_e32 v252, 16, v138
	v_and_b32_e32 v253, 0xffff0000, v138
	v_pk_mul_f32 v[124:125], v[124:125], v[252:253]
	v_lshlrev_b32_e32 v178, 16, v139
	v_and_b32_e32 v179, 0xffff0000, v139
	v_pk_mul_f32 v[126:127], v[126:127], v[178:179]
	v_lshlrev_b32_e32 v240, 16, v28
	v_and_b32_e32 v241, 0xffff0000, v28
	v_pk_add_f32 v[120:121], v[120:121], v[240:241]
	v_lshlrev_b32_e32 v244, 16, v29
	v_and_b32_e32 v245, 0xffff0000, v29
	v_pk_add_f32 v[122:123], v[122:123], v[244:245]
	v_lshlrev_b32_e32 v246, 16, v30
	v_and_b32_e32 v247, 0xffff0000, v30
	v_pk_add_f32 v[124:125], v[124:125], v[246:247]
	v_lshlrev_b32_e32 v252, 16, v31
	v_and_b32_e32 v253, 0xffff0000, v31
	v_pk_add_f32 v[126:127], v[126:127], v[252:253]
	v_cvt_pk_bf16_f32 v136, v120, v121
	v_cvt_pk_bf16_f32 v137, v122, v123
	v_cvt_pk_bf16_f32 v138, v124, v125
	v_cvt_pk_bf16_f32 v139, v126, v127
	s_mov_b32 s58, 0x58000
	v_lshl_add_u64 v[178:179], v[172:173], 0, s[58:59]
	global_store_dwordx4 v[178:179], v[136:139], off offset:256 sc1
	s_branch .Lmepi_done
.Lmepi_z0:
	global_load_dwordx4 v[128:131], v[170:171], off nt
	global_load_dwordx4 v[132:135], v[170:171], off offset:256 nt
	s_mov_b32 s58, 0x20000
	v_lshl_add_u64 v[244:245], v[170:171], 0, s[58:59]
	global_load_dwordx4 v[136:139], v[244:245], off nt
	global_load_dwordx4 v[140:143], v[244:245], off offset:256 nt
	s_mov_b32 s58, 0x40000
	v_lshl_add_u64 v[246:247], v[170:171], 0, s[58:59]
	global_load_dwordx4 v[144:147], v[246:247], off nt
	global_load_dwordx4 v[148:151], v[246:247], off offset:256 nt
	s_mov_b32 s58, 0x60000
	v_lshl_add_u64 v[252:253], v[170:171], 0, s[58:59]
	global_load_dwordx4 v[152:155], v[252:253], off nt
	global_load_dwordx4 v[156:159], v[252:253], off offset:256 nt
	s_mov_b32 s58, 0x100000
	v_lshl_add_u64 v[178:179], v[170:171], 0, s[58:59]
	global_load_dwordx4 v[180:183], v[178:179], off nt
	global_load_dwordx4 v[184:187], v[178:179], off offset:256 nt
	s_mov_b32 s58, 0x120000
	v_lshl_add_u64 v[240:241], v[170:171], 0, s[58:59]
	global_load_dwordx4 v[188:191], v[240:241], off nt
	global_load_dwordx4 v[192:195], v[240:241], off offset:256 nt
	s_mov_b32 s58, 0x140000
	v_lshl_add_u64 v[244:245], v[170:171], 0, s[58:59]
	global_load_dwordx4 v[196:199], v[244:245], off nt
	global_load_dwordx4 v[236:239], v[244:245], off offset:256 nt
	s_waitcnt vmcnt(13)
	v_lshlrev_b32_e32 v246, 16, v128
	v_and_b32_e32 v247, 0xffff0000, v128
	v_pk_mul_f32 v[0:1], v[0:1], v[246:247]
	v_lshlrev_b32_e32 v252, 16, v129
	v_and_b32_e32 v253, 0xffff0000, v129
	v_pk_mul_f32 v[2:3], v[2:3], v[252:253]
	v_lshlrev_b32_e32 v178, 16, v130
	v_and_b32_e32 v179, 0xffff0000, v130
	v_pk_mul_f32 v[4:5], v[4:5], v[178:179]
	v_lshlrev_b32_e32 v240, 16, v131
	v_and_b32_e32 v241, 0xffff0000, v131
	v_pk_mul_f32 v[6:7], v[6:7], v[240:241]
	v_cvt_pk_bf16_f32 v200, v0, v1
	v_cvt_pk_bf16_f32 v201, v2, v3
	v_cvt_pk_bf16_f32 v202, v4, v5
	v_cvt_pk_bf16_f32 v203, v6, v7
	s_waitcnt vmcnt(12)
	v_lshlrev_b32_e32 v244, 16, v132
	v_and_b32_e32 v245, 0xffff0000, v132
	v_pk_mul_f32 v[8:9], v[8:9], v[244:245]
	v_lshlrev_b32_e32 v246, 16, v133
	v_and_b32_e32 v247, 0xffff0000, v133
	v_pk_mul_f32 v[10:11], v[10:11], v[246:247]
	v_lshlrev_b32_e32 v252, 16, v134
	v_and_b32_e32 v253, 0xffff0000, v134
	v_pk_mul_f32 v[12:13], v[12:13], v[252:253]
	v_lshlrev_b32_e32 v178, 16, v135
	v_and_b32_e32 v179, 0xffff0000, v135
	v_pk_mul_f32 v[14:15], v[14:15], v[178:179]
	v_cvt_pk_bf16_f32 v204, v8, v9
	v_cvt_pk_bf16_f32 v205, v10, v11
	v_cvt_pk_bf16_f32 v206, v12, v13
	v_cvt_pk_bf16_f32 v207, v14, v15
	s_mov_b32 s58, 0x160000
	v_lshl_add_u64 v[240:241], v[170:171], 0, s[58:59]
	global_load_dwordx4 v[0:3], v[240:241], off nt
	global_load_dwordx4 v[4:7], v[240:241], off offset:256 nt
	s_waitcnt vmcnt(13)
	v_lshlrev_b32_e32 v244, 16, v136
	v_and_b32_e32 v245, 0xffff0000, v136
	v_pk_mul_f32 v[16:17], v[16:17], v[244:245]
	v_lshlrev_b32_e32 v246, 16, v137
	v_and_b32_e32 v247, 0xffff0000, v137
	v_pk_mul_f32 v[18:19], v[18:19], v[246:247]
	v_lshlrev_b32_e32 v252, 16, v138
	v_and_b32_e32 v253, 0xffff0000, v138
	v_pk_mul_f32 v[20:21], v[20:21], v[252:253]
	v_lshlrev_b32_e32 v178, 16, v139
	v_and_b32_e32 v179, 0xffff0000, v139
	v_pk_mul_f32 v[22:23], v[22:23], v[178:179]
	v_cvt_pk_bf16_f32 v208, v16, v17
	v_cvt_pk_bf16_f32 v209, v18, v19
	v_cvt_pk_bf16_f32 v210, v20, v21
	v_cvt_pk_bf16_f32 v211, v22, v23
	s_waitcnt vmcnt(12)
	v_lshlrev_b32_e32 v240, 16, v140
	v_and_b32_e32 v241, 0xffff0000, v140
	v_pk_mul_f32 v[24:25], v[24:25], v[240:241]
	v_lshlrev_b32_e32 v244, 16, v141
	v_and_b32_e32 v245, 0xffff0000, v141
	v_pk_mul_f32 v[26:27], v[26:27], v[244:245]
	v_lshlrev_b32_e32 v246, 16, v142
	v_and_b32_e32 v247, 0xffff0000, v142
	v_pk_mul_f32 v[28:29], v[28:29], v[246:247]
	v_lshlrev_b32_e32 v252, 16, v143
	v_and_b32_e32 v253, 0xffff0000, v143
	v_pk_mul_f32 v[30:31], v[30:31], v[252:253]
	v_cvt_pk_bf16_f32 v212, v24, v25
	v_cvt_pk_bf16_f32 v213, v26, v27
	v_cvt_pk_bf16_f32 v214, v28, v29
	v_cvt_pk_bf16_f32 v215, v30, v31
	s_waitcnt vmcnt(11)
	v_lshlrev_b32_e32 v178, 16, v144
	v_and_b32_e32 v179, 0xffff0000, v144
	v_pk_mul_f32 v[32:33], v[32:33], v[178:179]
	v_lshlrev_b32_e32 v240, 16, v145
	v_and_b32_e32 v241, 0xffff0000, v145
	v_pk_mul_f32 v[34:35], v[34:35], v[240:241]
	v_lshlrev_b32_e32 v244, 16, v146
	v_and_b32_e32 v245, 0xffff0000, v146
	v_pk_mul_f32 v[36:37], v[36:37], v[244:245]
	v_lshlrev_b32_e32 v246, 16, v147
	v_and_b32_e32 v247, 0xffff0000, v147
	v_pk_mul_f32 v[38:39], v[38:39], v[246:247]
	v_cvt_pk_bf16_f32 v216, v32, v33
	v_cvt_pk_bf16_f32 v217, v34, v35
	v_cvt_pk_bf16_f32 v218, v36, v37
	v_cvt_pk_bf16_f32 v219, v38, v39
	s_waitcnt vmcnt(10)
	v_lshlrev_b32_e32 v252, 16, v148
	v_and_b32_e32 v253, 0xffff0000, v148
	v_pk_mul_f32 v[40:41], v[40:41], v[252:253]
	v_lshlrev_b32_e32 v178, 16, v149
	v_and_b32_e32 v179, 0xffff0000, v149
	v_pk_mul_f32 v[42:43], v[42:43], v[178:179]
	v_lshlrev_b32_e32 v240, 16, v150
	v_and_b32_e32 v241, 0xffff0000, v150
	v_pk_mul_f32 v[44:45], v[44:45], v[240:241]
	v_lshlrev_b32_e32 v244, 16, v151
	v_and_b32_e32 v245, 0xffff0000, v151
	v_pk_mul_f32 v[46:47], v[46:47], v[244:245]
	v_cvt_pk_bf16_f32 v220, v40, v41
	v_cvt_pk_bf16_f32 v221, v42, v43
	v_cvt_pk_bf16_f32 v222, v44, v45
	v_cvt_pk_bf16_f32 v223, v46, v47
	s_waitcnt vmcnt(9)
	v_lshlrev_b32_e32 v246, 16, v152
	v_and_b32_e32 v247, 0xffff0000, v152
	v_pk_mul_f32 v[48:49], v[48:49], v[246:247]
	v_lshlrev_b32_e32 v252, 16, v153
	v_and_b32_e32 v253, 0xffff0000, v153
	v_pk_mul_f32 v[50:51], v[50:51], v[252:253]
	v_lshlrev_b32_e32 v178, 16, v154
	v_and_b32_e32 v179, 0xffff0000, v154
	v_pk_mul_f32 v[52:53], v[52:53], v[178:179]
	v_lshlrev_b32_e32 v240, 16, v155
	v_and_b32_e32 v241, 0xffff0000, v155
	v_pk_mul_f32 v[54:55], v[54:55], v[240:241]
	v_cvt_pk_bf16_f32 v224, v48, v49
	v_cvt_pk_bf16_f32 v225, v50, v51
	v_cvt_pk_bf16_f32 v226, v52, v53
	v_cvt_pk_bf16_f32 v227, v54, v55
	s_waitcnt vmcnt(8)
	v_lshlrev_b32_e32 v244, 16, v156
	v_and_b32_e32 v245, 0xffff0000, v156
	v_pk_mul_f32 v[56:57], v[56:57], v[244:245]
	v_lshlrev_b32_e32 v246, 16, v157
	v_and_b32_e32 v247, 0xffff0000, v157
	v_pk_mul_f32 v[58:59], v[58:59], v[246:247]
	v_lshlrev_b32_e32 v252, 16, v158
	v_and_b32_e32 v253, 0xffff0000, v158
	v_pk_mul_f32 v[60:61], v[60:61], v[252:253]
	v_lshlrev_b32_e32 v178, 16, v159
	v_and_b32_e32 v179, 0xffff0000, v159
	v_pk_mul_f32 v[62:63], v[62:63], v[178:179]
	v_cvt_pk_bf16_f32 v156, v56, v57
	v_cvt_pk_bf16_f32 v157, v58, v59
	v_cvt_pk_bf16_f32 v158, v60, v61
	v_cvt_pk_bf16_f32 v159, v62, v63
	s_mov_b32 s58, 0x18000
	v_lshl_add_u64 v[240:241], v[172:173], 0, s[58:59]
	global_store_dwordx4 v[240:241], v[156:159], off offset:256
	s_waitcnt vmcnt(8)
	v_lshlrev_b32_e32 v244, 16, v180
	v_and_b32_e32 v245, 0xffff0000, v180
	v_pk_mul_f32 v[64:65], v[64:65], v[244:245]
	v_lshlrev_b32_e32 v246, 16, v181
	v_and_b32_e32 v247, 0xffff0000, v181
	v_pk_mul_f32 v[66:67], v[66:67], v[246:247]
	v_lshlrev_b32_e32 v252, 16, v182
	v_and_b32_e32 v253, 0xffff0000, v182
	v_pk_mul_f32 v[68:69], v[68:69], v[252:253]
	v_lshlrev_b32_e32 v178, 16, v183
	v_and_b32_e32 v179, 0xffff0000, v183
	v_pk_mul_f32 v[70:71], v[70:71], v[178:179]
	v_cvt_pk_bf16_f32 v180, v64, v65
	v_cvt_pk_bf16_f32 v181, v66, v67
	v_cvt_pk_bf16_f32 v182, v68, v69
	v_cvt_pk_bf16_f32 v183, v70, v71
	s_mov_b32 s58, 0x40000
	v_lshl_add_u64 v[240:241], v[172:173], 0, s[58:59]
	global_store_dwordx4 v[240:241], v[180:183], off
	s_waitcnt vmcnt(8)
	v_lshlrev_b32_e32 v244, 16, v184
	v_and_b32_e32 v245, 0xffff0000, v184
	v_pk_mul_f32 v[72:73], v[72:73], v[244:245]
	v_lshlrev_b32_e32 v246, 16, v185
	v_and_b32_e32 v247, 0xffff0000, v185
	v_pk_mul_f32 v[74:75], v[74:75], v[246:247]
	v_lshlrev_b32_e32 v252, 16, v186
	v_and_b32_e32 v253, 0xffff0000, v186
	v_pk_mul_f32 v[76:77], v[76:77], v[252:253]
	v_lshlrev_b32_e32 v178, 16, v187
	v_and_b32_e32 v179, 0xffff0000, v187
	v_pk_mul_f32 v[78:79], v[78:79], v[178:179]
	v_cvt_pk_bf16_f32 v184, v72, v73
	v_cvt_pk_bf16_f32 v185, v74, v75
	v_cvt_pk_bf16_f32 v186, v76, v77
	v_cvt_pk_bf16_f32 v187, v78, v79
	s_mov_b32 s58, 0x40000
	v_lshl_add_u64 v[240:241], v[172:173], 0, s[58:59]
	global_store_dwordx4 v[240:241], v[184:187], off offset:256
	s_waitcnt vmcnt(8)
	v_lshlrev_b32_e32 v244, 16, v188
	v_and_b32_e32 v245, 0xffff0000, v188
	v_pk_mul_f32 v[80:81], v[80:81], v[244:245]
	v_lshlrev_b32_e32 v246, 16, v189
	v_and_b32_e32 v247, 0xffff0000, v189
	v_pk_mul_f32 v[82:83], v[82:83], v[246:247]
	v_lshlrev_b32_e32 v252, 16, v190
	v_and_b32_e32 v253, 0xffff0000, v190
	v_pk_mul_f32 v[84:85], v[84:85], v[252:253]
	v_lshlrev_b32_e32 v178, 16, v191
	v_and_b32_e32 v179, 0xffff0000, v191
	v_pk_mul_f32 v[86:87], v[86:87], v[178:179]
	v_cvt_pk_bf16_f32 v188, v80, v81
	v_cvt_pk_bf16_f32 v189, v82, v83
	v_cvt_pk_bf16_f32 v190, v84, v85
	v_cvt_pk_bf16_f32 v191, v86, v87
	s_mov_b32 s58, 0x48000
	v_lshl_add_u64 v[240:241], v[172:173], 0, s[58:59]
	global_store_dwordx4 v[240:241], v[188:191], off
	s_waitcnt vmcnt(8)
	v_lshlrev_b32_e32 v244, 16, v192
	v_and_b32_e32 v245, 0xffff0000, v192
	v_pk_mul_f32 v[88:89], v[88:89], v[244:245]
	v_lshlrev_b32_e32 v246, 16, v193
	v_and_b32_e32 v247, 0xffff0000, v193
	v_pk_mul_f32 v[90:91], v[90:91], v[246:247]
	v_lshlrev_b32_e32 v252, 16, v194
	v_and_b32_e32 v253, 0xffff0000, v194
	v_pk_mul_f32 v[92:93], v[92:93], v[252:253]
	v_lshlrev_b32_e32 v178, 16, v195
	v_and_b32_e32 v179, 0xffff0000, v195
	v_pk_mul_f32 v[94:95], v[94:95], v[178:179]
	v_cvt_pk_bf16_f32 v192, v88, v89
	v_cvt_pk_bf16_f32 v193, v90, v91
	v_cvt_pk_bf16_f32 v194, v92, v93
	v_cvt_pk_bf16_f32 v195, v94, v95
	s_mov_b32 s58, 0x48000
	v_lshl_add_u64 v[240:241], v[172:173], 0, s[58:59]
	global_store_dwordx4 v[240:241], v[192:195], off offset:256
	s_waitcnt vmcnt(8)
	v_lshlrev_b32_e32 v244, 16, v196
	v_and_b32_e32 v245, 0xffff0000, v196
	v_pk_mul_f32 v[96:97], v[96:97], v[244:245]
	v_lshlrev_b32_e32 v246, 16, v197
	v_and_b32_e32 v247, 0xffff0000, v197
	v_pk_mul_f32 v[98:99], v[98:99], v[246:247]
	v_lshlrev_b32_e32 v252, 16, v198
	v_and_b32_e32 v253, 0xffff0000, v198
	v_pk_mul_f32 v[100:101], v[100:101], v[252:253]
	v_lshlrev_b32_e32 v178, 16, v199
	v_and_b32_e32 v179, 0xffff0000, v199
	v_pk_mul_f32 v[102:103], v[102:103], v[178:179]
	v_cvt_pk_bf16_f32 v196, v96, v97
	v_cvt_pk_bf16_f32 v197, v98, v99
	v_cvt_pk_bf16_f32 v198, v100, v101
	v_cvt_pk_bf16_f32 v199, v102, v103
	s_mov_b32 s58, 0x50000
	v_lshl_add_u64 v[240:241], v[172:173], 0, s[58:59]
	global_store_dwordx4 v[240:241], v[196:199], off
	s_waitcnt vmcnt(8)
	v_lshlrev_b32_e32 v244, 16, v236
	v_and_b32_e32 v245, 0xffff0000, v236
	v_pk_mul_f32 v[104:105], v[104:105], v[244:245]
	v_lshlrev_b32_e32 v246, 16, v237
	v_and_b32_e32 v247, 0xffff0000, v237
	v_pk_mul_f32 v[106:107], v[106:107], v[246:247]
	v_lshlrev_b32_e32 v252, 16, v238
	v_and_b32_e32 v253, 0xffff0000, v238
	v_pk_mul_f32 v[108:109], v[108:109], v[252:253]
	v_lshlrev_b32_e32 v178, 16, v239
	v_and_b32_e32 v179, 0xffff0000, v239
	v_pk_mul_f32 v[110:111], v[110:111], v[178:179]
	v_cvt_pk_bf16_f32 v236, v104, v105
	v_cvt_pk_bf16_f32 v237, v106, v107
	v_cvt_pk_bf16_f32 v238, v108, v109
	v_cvt_pk_bf16_f32 v239, v110, v111
	s_mov_b32 s58, 0x50000
	v_lshl_add_u64 v[240:241], v[172:173], 0, s[58:59]
	global_store_dwordx4 v[240:241], v[236:239], off offset:256
	s_waitcnt vmcnt(8)
	v_lshlrev_b32_e32 v244, 16, v0
	v_and_b32_e32 v245, 0xffff0000, v0
	v_pk_mul_f32 v[112:113], v[112:113], v[244:245]
	v_lshlrev_b32_e32 v246, 16, v1
	v_and_b32_e32 v247, 0xffff0000, v1
	v_pk_mul_f32 v[114:115], v[114:115], v[246:247]
	v_lshlrev_b32_e32 v252, 16, v2
	v_and_b32_e32 v253, 0xffff0000, v2
	v_pk_mul_f32 v[116:117], v[116:117], v[252:253]
	v_lshlrev_b32_e32 v178, 16, v3
	v_and_b32_e32 v179, 0xffff0000, v3
	v_pk_mul_f32 v[118:119], v[118:119], v[178:179]
	v_cvt_pk_bf16_f32 v0, v112, v113
	v_cvt_pk_bf16_f32 v1, v114, v115
	v_cvt_pk_bf16_f32 v2, v116, v117
	v_cvt_pk_bf16_f32 v3, v118, v119
	s_mov_b32 s58, 0x58000
	v_lshl_add_u64 v[240:241], v[172:173], 0, s[58:59]
	global_store_dwordx4 v[240:241], v[0:3], off
	s_waitcnt vmcnt(8)
	v_lshlrev_b32_e32 v244, 16, v4
	v_and_b32_e32 v245, 0xffff0000, v4
	v_pk_mul_f32 v[120:121], v[120:121], v[244:245]
	v_lshlrev_b32_e32 v246, 16, v5
	v_and_b32_e32 v247, 0xffff0000, v5
	v_pk_mul_f32 v[122:123], v[122:123], v[246:247]
	v_lshlrev_b32_e32 v252, 16, v6
	v_and_b32_e32 v253, 0xffff0000, v6
	v_pk_mul_f32 v[124:125], v[124:125], v[252:253]
	v_lshlrev_b32_e32 v178, 16, v7
	v_and_b32_e32 v179, 0xffff0000, v7
	v_pk_mul_f32 v[126:127], v[126:127], v[178:179]
	v_cvt_pk_bf16_f32 v4, v120, v121
	v_cvt_pk_bf16_f32 v5, v122, v123
	v_cvt_pk_bf16_f32 v6, v124, v125
	v_cvt_pk_bf16_f32 v7, v126, v127
	s_mov_b32 s58, 0x58000
	v_lshl_add_u64 v[240:241], v[172:173], 0, s[58:59]
	global_store_dwordx4 v[240:241], v[4:7], off offset:256
